# stack + P2 gate/cumsum arithmetic: 256 broadcast LDS reads issued one step (4 reads) ahead into a register ring v[220:251], consumers renamed, lgkmcnt recomputed
# speedup vs baseline: 1.0013x; 1.0013x over previous
.LBB0_269:
	s_ashr_i32 s46, s44, 2
	s_ashr_i32 s47, s46, 31
	s_and_b32 s45, s44, 3
	s_lshl_b64 s[48:49], s[46:47], 14
	v_lshl_or_b32 v114, s45, 7, v84
	v_lshl_add_u64 v[2:3], v[66:67], 0, s[48:49]
	v_add_co_u32_e32 v4, vcc, 0x2000, v2
	v_lshlrev_b32_e32 v64, 2, v114
	s_nop 0
	v_addc_co_u32_e32 v5, vcc, 0, v3, vcc
	v_lshl_add_u64 v[14:15], s[16:17], 0, v[64:65]
	s_barrier
	global_load_dwordx4 v[20:23], v[2:3], off
	global_load_dwordx4 v[24:27], v[4:5], off
	v_add_co_u32_e32 v4, vcc, 0x1000, v14
	global_load_dword v2, v64, s[16:17] offset:2048
	s_nop 0
	v_addc_co_u32_e32 v5, vcc, 0, v15, vcc
	v_add_co_u32_e32 v6, vcc, s61, v14
	s_lshl_b32 s0, s45, 8
	s_nop 0
	v_addc_co_u32_e32 v7, vcc, 0, v15, vcc
	v_add_co_u32_e32 v16, vcc, 0x3000, v14
	s_mov_b64 s[50:51], 0
	s_nop 0
	v_addc_co_u32_e32 v17, vcc, 0, v15, vcc
	v_add_co_u32_e32 v18, vcc, 0x4000, v14
	s_nop 1
	v_addc_co_u32_e32 v19, vcc, 0, v15, vcc
	global_load_dword v10, v[4:5], off
	global_load_dword v12, v[4:5], off offset:2048
	global_load_dword v8, v[6:7], off
	global_load_dword v11, v[6:7], off offset:2048
	s_nop 0
	global_load_dword v7, v[16:17], off
	global_load_dword v9, v[16:17], off offset:2048
	global_load_dword v3, v[18:19], off
	global_load_dword v4, v[18:19], off offset:2048
	v_add_co_u32_e32 v16, vcc, 0x5000, v14
	s_nop 1
	v_addc_co_u32_e32 v17, vcc, 0, v15, vcc
	global_load_dword v5, v[16:17], off
	global_load_dword v6, v[16:17], off offset:2048
	s_nop 0
	global_load_dword v17, v64, s[16:17]
	v_add_co_u32_e32 v28, vcc, 0x6000, v14
	global_load_dword v18, v64, s[18:19]
	s_nop 0
	v_addc_co_u32_e32 v29, vcc, 0, v15, vcc
	v_add_co_u32_e32 v30, vcc, 0x7000, v14
	s_nop 1
	v_addc_co_u32_e32 v31, vcc, 0, v15, vcc
	global_load_dword v16, v[28:29], off offset:2048
	global_load_dword v14, v[28:29], off
	global_load_dword v15, v[30:31], off offset:2048
	global_load_dword v13, v[30:31], off
	s_waitcnt vmcnt(18)
	ds_write_b128 v86, v[20:23]
	s_waitcnt vmcnt(17)
	ds_write_b128 v86, v[24:27] offset:8192
	s_waitcnt lgkmcnt(0)
	s_barrier
	ds_read_b128 v[220:223], v63
	ds_read_b128 v[224:227], v63 offset:16
	ds_read_b128 v[228:231], v63 offset:32
	ds_read_b128 v[232:235], v63 offset:48
	ds_read_b128 v[236:239], v63 offset:64
	ds_read_b128 v[240:243], v63 offset:80
	ds_read_b128 v[244:247], v63 offset:96
	ds_read_b128 v[248:251], v63 offset:112
	s_waitcnt vmcnt(16) lgkmcnt(7)
	v_mul_f32_e32 v19, v221, v2
	s_waitcnt vmcnt(14)
	v_mul_f32_e32 v21, v223, v12
	v_fmac_f32_e32 v21, v222, v10
	s_waitcnt vmcnt(12) lgkmcnt(6)
	v_mul_f32_e32 v23, v225, v11
	v_fmac_f32_e32 v23, v224, v8
	s_waitcnt vmcnt(10)
	v_mul_f32_e32 v25, v227, v9
	v_fmac_f32_e32 v25, v226, v7
	s_waitcnt vmcnt(8) lgkmcnt(5)
	v_mul_f32_e32 v27, v229, v4
	v_fmac_f32_e32 v27, v228, v3
	s_waitcnt vmcnt(6)
	v_mul_f32_e32 v29, v231, v6
	s_waitcnt vmcnt(5)
	v_fmac_f32_e32 v19, v220, v17
	v_add_f32_e32 v19, v19, v21
	v_fmac_f32_e32 v29, v230, v5
	v_add_f32_e32 v20, v23, v25
	s_waitcnt vmcnt(4)
	v_add_f32_e32 v19, v18, v19
	v_add_f32_e32 v21, v27, v29
	v_add_f32_e32 v19, v19, v20
	v_add_f32_e32 v19, v19, v21
	s_waitcnt vmcnt(3) lgkmcnt(4)
	v_mul_f32_e32 v20, v233, v16
	s_waitcnt vmcnt(2)
	v_fmac_f32_e32 v20, v232, v14
	s_waitcnt vmcnt(1)
	v_mul_f32_e32 v21, v235, v15
	s_waitcnt vmcnt(0)
	v_lshl_add_u32 v218, s46, 8, v88
	s_mov_b32 s100, 0x30000
	s_mov_b32 s101, 0
	v_mad_i64_i32 v[218:219], s[98:99], v218, s66, v[68:69]
	v_lshl_add_u64 v[218:219], v[218:219], 0, s[0:1]
	v_lshl_add_u64 v[218:219], v[218:219], 0, v[70:71]
	global_load_dwordx4 v[186:189], v[218:219], off
	v_lshl_add_u64 v[218:219], v[218:219], 0, s[100:101]
	global_load_dwordx4 v[190:193], v[218:219], off
	v_lshl_add_u64 v[218:219], v[218:219], 0, s[100:101]
	global_load_dwordx4 v[194:197], v[218:219], off
	v_lshl_add_u64 v[218:219], v[218:219], 0, s[100:101]
	global_load_dwordx4 v[198:201], v[218:219], off
	v_lshl_add_u64 v[218:219], v[218:219], 0, s[100:101]
	global_load_dwordx4 v[202:205], v[218:219], off
	v_lshl_add_u64 v[218:219], v[218:219], 0, s[100:101]
	global_load_dwordx4 v[206:209], v[218:219], off
	v_lshl_add_u64 v[218:219], v[218:219], 0, s[100:101]
	global_load_dwordx4 v[210:213], v[218:219], off
	v_lshl_add_u64 v[218:219], v[218:219], 0, s[100:101]
	global_load_dwordx4 v[214:217], v[218:219], off
	v_fmac_f32_e32 v21, v234, v13
	v_add_f32_e32 v20, v20, v21
	v_add_f32_e32 v19, v19, v20
	v_mul_f32_e64 v20, |v19|, s64
	v_exp_f32_e32 v24, v20
	ds_read_b128 v[220:223], v63 offset:128
	v_min_f32_e32 v19, 0, v19
	v_add_f32_e32 v24, 1.0, v24
	v_log_f32_e32 v28, v24
	ds_read_b128 v[224:227], v63 offset:144
	s_waitcnt lgkmcnt(5)
	v_mul_f32_e32 v21, v237, v2
	v_fmac_f32_e32 v21, v236, v17
	v_mul_f32_e32 v20, v239, v12
	v_fmac_f32_e32 v20, v238, v10
	v_add_f32_e32 v20, v21, v20
	s_waitcnt lgkmcnt(4)
	v_mul_f32_e32 v25, v241, v11
	v_add_f32_e32 v29, v18, v20
	v_fmac_f32_e32 v25, v240, v8
	v_mul_f32_e32 v24, v243, v9
	ds_read_b128 v[228:231], v63 offset:160
	v_fmac_f32_e32 v24, v242, v7
	v_add_f32_e32 v24, v25, v24
	v_add_f32_e32 v29, v29, v24
	ds_read_b128 v[232:235], v63 offset:176
	s_waitcnt lgkmcnt(5)
	v_mul_f32_e32 v21, v245, v4
	v_fmac_f32_e32 v21, v244, v3
	v_mul_f32_e32 v20, v247, v6
	v_fmac_f32_e32 v20, v246, v5
	v_add_f32_e32 v20, v21, v20
	s_waitcnt lgkmcnt(4)
	v_mul_f32_e32 v21, v249, v16
	v_mul_f32_e32 v22, v251, v15
	v_fmac_f32_e32 v21, v248, v14
	v_fmac_f32_e32 v22, v250, v13
	v_add_f32_e32 v20, v29, v20
	v_add_f32_e32 v21, v21, v22
	v_add_f32_e32 v24, v20, v21
	v_mul_f32_e64 v20, |v24|, s64
	v_exp_f32_e32 v20, v20
	v_fmac_f32_e32 v19, 0xbf317218, v28
	v_min_f32_e32 v28, 0, v24
	v_fma_f32 v19, v19, s65, 0
	v_add_f32_e32 v20, 1.0, v20
	v_log_f32_e32 v25, v20
	ds_read_b128 v[236:239], v63 offset:192
	v_fmac_f32_e32 v28, 0xbf317218, v25
	ds_read_b128 v[240:243], v63 offset:208
	s_waitcnt lgkmcnt(5)
	v_mul_f32_e32 v21, v221, v2
	v_fmac_f32_e32 v21, v220, v17
	v_mul_f32_e32 v20, v223, v12
	v_fmac_f32_e32 v20, v222, v10
	v_add_f32_e32 v20, v21, v20
	s_waitcnt lgkmcnt(4)
	v_mul_f32_e32 v25, v225, v11
	v_add_f32_e32 v29, v18, v20
	v_fmac_f32_e32 v25, v224, v8
	v_mul_f32_e32 v24, v227, v9
	ds_read_b128 v[244:247], v63 offset:224
	v_fmac_f32_e32 v24, v226, v7
	v_add_f32_e32 v24, v25, v24
	v_add_f32_e32 v29, v29, v24
	ds_read_b128 v[248:251], v63 offset:240
	s_waitcnt lgkmcnt(5)
	v_mul_f32_e32 v21, v229, v4
	v_fmac_f32_e32 v21, v228, v3
	v_mul_f32_e32 v20, v231, v6
	v_fmac_f32_e32 v20, v230, v5
	v_add_f32_e32 v20, v21, v20
	s_waitcnt lgkmcnt(4)
	v_mul_f32_e32 v21, v233, v16
	v_mul_f32_e32 v22, v235, v15
	v_fmac_f32_e32 v21, v232, v14
	v_fmac_f32_e32 v22, v234, v13
	v_add_f32_e32 v20, v29, v20
	v_add_f32_e32 v21, v21, v22
	v_add_f32_e32 v21, v20, v21
	v_mul_f32_e64 v20, |v21|, s64
	v_exp_f32_e32 v26, v20
	ds_read_b128 v[220:223], v63 offset:256
	v_fmamk_f32 v20, v28, 0x3d800000, v19
	v_min_f32_e32 v21, 0, v21
	v_add_f32_e32 v26, 1.0, v26
	v_log_f32_e32 v30, v26
	ds_read_b128 v[224:227], v63 offset:272
	s_waitcnt lgkmcnt(5)
	v_mul_f32_e32 v23, v237, v2
	v_fmac_f32_e32 v23, v236, v17
	v_mul_f32_e32 v22, v239, v12
	v_fmac_f32_e32 v22, v238, v10
	v_add_f32_e32 v22, v23, v22
	s_waitcnt lgkmcnt(4)
	v_mul_f32_e32 v27, v241, v11
	v_add_f32_e32 v31, v18, v22
	v_fmac_f32_e32 v27, v240, v8
	v_mul_f32_e32 v26, v243, v9
	ds_read_b128 v[228:231], v63 offset:288
	v_fmac_f32_e32 v26, v242, v7
	v_add_f32_e32 v26, v27, v26
	v_add_f32_e32 v31, v31, v26
	ds_read_b128 v[232:235], v63 offset:304
	s_waitcnt lgkmcnt(5)
	v_mul_f32_e32 v23, v245, v4
	v_fmac_f32_e32 v23, v244, v3
	v_mul_f32_e32 v22, v247, v6
	v_fmac_f32_e32 v22, v246, v5
	v_add_f32_e32 v22, v23, v22
	s_waitcnt lgkmcnt(4)
	v_mul_f32_e32 v23, v249, v16
	v_mul_f32_e32 v24, v251, v15
	v_fmac_f32_e32 v23, v248, v14
	v_fmac_f32_e32 v24, v250, v13
	v_add_f32_e32 v22, v31, v22
	v_add_f32_e32 v23, v23, v24
	v_add_f32_e32 v31, v22, v23
	v_mul_f32_e64 v22, |v31|, s64
	v_exp_f32_e32 v26, v22
	ds_read_b128 v[236:239], v63 offset:320
	v_fmac_f32_e32 v21, 0xbf317218, v30
	v_min_f32_e32 v31, 0, v31
	v_add_f32_e32 v26, 1.0, v26
	v_log_f32_e32 v30, v26
	ds_read_b128 v[240:243], v63 offset:336
	s_waitcnt lgkmcnt(5)
	v_mul_f32_e32 v23, v221, v2
	v_fmac_f32_e32 v23, v220, v17
	v_mul_f32_e32 v22, v223, v12
	v_fmac_f32_e32 v22, v222, v10
	v_add_f32_e32 v22, v23, v22
	s_waitcnt lgkmcnt(4)
	v_mul_f32_e32 v27, v225, v11
	v_add_f32_e32 v32, v18, v22
	v_fmac_f32_e32 v27, v224, v8
	v_mul_f32_e32 v26, v227, v9
	ds_read_b128 v[244:247], v63 offset:352
	v_fmac_f32_e32 v26, v226, v7
	v_add_f32_e32 v26, v27, v26
	v_add_f32_e32 v32, v32, v26
	ds_read_b128 v[248:251], v63 offset:368
	s_waitcnt lgkmcnt(5)
	v_mul_f32_e32 v23, v229, v4
	v_fmac_f32_e32 v23, v228, v3
	v_mul_f32_e32 v22, v231, v6
	v_fmac_f32_e32 v22, v230, v5
	v_add_f32_e32 v22, v23, v22
	s_waitcnt lgkmcnt(4)
	v_mul_f32_e32 v23, v233, v16
	v_mul_f32_e32 v24, v235, v15
	v_fmac_f32_e32 v23, v232, v14
	v_fmac_f32_e32 v24, v234, v13
	v_add_f32_e32 v22, v32, v22
	v_add_f32_e32 v23, v23, v24
	v_add_f32_e32 v32, v22, v23
	v_mul_f32_e64 v22, |v32|, s64
	v_exp_f32_e32 v26, v22
	ds_read_b128 v[220:223], v63 offset:384
	v_fmac_f32_e32 v31, 0xbf317218, v30
	v_fmamk_f32 v21, v21, 0x3d800000, v20
	v_add_f32_e32 v26, 1.0, v26
	v_log_f32_e32 v30, v26
	ds_read_b128 v[224:227], v63 offset:400
	s_waitcnt lgkmcnt(5)
	v_mul_f32_e32 v23, v237, v2
	v_fmac_f32_e32 v23, v236, v17
	v_mul_f32_e32 v22, v239, v12
	v_fmac_f32_e32 v22, v238, v10
	v_add_f32_e32 v22, v23, v22
	s_waitcnt lgkmcnt(4)
	v_mul_f32_e32 v27, v241, v11
	v_add_f32_e32 v33, v18, v22
	v_fmac_f32_e32 v27, v240, v8
	v_mul_f32_e32 v26, v243, v9
	ds_read_b128 v[228:231], v63 offset:416
	v_fmac_f32_e32 v26, v242, v7
	v_add_f32_e32 v26, v27, v26
	v_add_f32_e32 v33, v33, v26
	ds_read_b128 v[232:235], v63 offset:432
	s_waitcnt lgkmcnt(5)
	v_mul_f32_e32 v23, v245, v4
	v_fmac_f32_e32 v23, v244, v3
	v_mul_f32_e32 v22, v247, v6
	v_fmac_f32_e32 v22, v246, v5
	v_add_f32_e32 v22, v23, v22
	s_waitcnt lgkmcnt(4)
	v_mul_f32_e32 v23, v249, v16
	v_mul_f32_e32 v24, v251, v15
	v_fmac_f32_e32 v23, v248, v14
	v_fmac_f32_e32 v24, v250, v13
	v_add_f32_e32 v22, v33, v22
	v_add_f32_e32 v23, v23, v24
	v_add_f32_e32 v28, v22, v23
	v_mul_f32_e64 v22, |v28|, s64
	v_exp_f32_e32 v23, v22
	v_min_f32_e32 v29, 0, v32
	v_fmac_f32_e32 v29, 0xbf317218, v30
	ds_read_b128 v[236:239], v63 offset:448
	v_add_f32_e32 v23, 1.0, v23
	v_log_f32_e32 v30, v23
	v_fmamk_f32 v22, v31, 0x3d800000, v21
	v_min_f32_e32 v32, 0, v28
	v_fmamk_f32 v23, v29, 0x3d800000, v22
	v_fmac_f32_e32 v32, 0xbf317218, v30
	ds_read_b128 v[240:243], v63 offset:464
	s_waitcnt lgkmcnt(5)
	v_mul_f32_e32 v25, v221, v2
	v_fmac_f32_e32 v25, v220, v17
	v_mul_f32_e32 v24, v223, v12
	v_fmac_f32_e32 v24, v222, v10
	v_add_f32_e32 v24, v25, v24
	s_waitcnt lgkmcnt(4)
	v_mul_f32_e32 v29, v225, v11
	v_add_f32_e32 v33, v18, v24
	v_fmac_f32_e32 v29, v224, v8
	v_mul_f32_e32 v28, v227, v9
	ds_read_b128 v[244:247], v63 offset:480
	v_fmac_f32_e32 v28, v226, v7
	v_add_f32_e32 v28, v29, v28
	v_add_f32_e32 v33, v33, v28
	ds_read_b128 v[248:251], v63 offset:496
	s_waitcnt lgkmcnt(5)
	v_mul_f32_e32 v25, v229, v4
	v_fmac_f32_e32 v25, v228, v3
	v_mul_f32_e32 v24, v231, v6
	v_fmac_f32_e32 v24, v230, v5
	v_add_f32_e32 v24, v25, v24
	s_waitcnt lgkmcnt(4)
	v_mul_f32_e32 v25, v233, v16
	v_mul_f32_e32 v26, v235, v15
	v_fmac_f32_e32 v25, v232, v14
	v_fmac_f32_e32 v26, v234, v13
	v_add_f32_e32 v24, v33, v24
	v_add_f32_e32 v25, v25, v26
	v_add_f32_e32 v25, v24, v25
	v_mul_f32_e64 v24, |v25|, s64
	v_exp_f32_e32 v30, v24
	ds_read_b128 v[220:223], v63 offset:512
	v_fmamk_f32 v24, v32, 0x3d800000, v23
	v_min_f32_e32 v25, 0, v25
	v_add_f32_e32 v30, 1.0, v30
	v_log_f32_e32 v34, v30
	ds_read_b128 v[224:227], v63 offset:528
	s_waitcnt lgkmcnt(5)
	v_mul_f32_e32 v27, v237, v2
	v_fmac_f32_e32 v27, v236, v17
	v_mul_f32_e32 v26, v239, v12
	v_fmac_f32_e32 v26, v238, v10
	v_add_f32_e32 v26, v27, v26
	s_waitcnt lgkmcnt(4)
	v_mul_f32_e32 v31, v241, v11
	v_add_f32_e32 v35, v18, v26
	v_fmac_f32_e32 v31, v240, v8
	v_mul_f32_e32 v30, v243, v9
	ds_read_b128 v[228:231], v63 offset:544
	v_fmac_f32_e32 v30, v242, v7
	v_add_f32_e32 v30, v31, v30
	v_add_f32_e32 v35, v35, v30
	ds_read_b128 v[232:235], v63 offset:560
	s_waitcnt lgkmcnt(5)
	v_mul_f32_e32 v27, v245, v4
	v_fmac_f32_e32 v27, v244, v3
	v_mul_f32_e32 v26, v247, v6
	v_fmac_f32_e32 v26, v246, v5
	v_add_f32_e32 v26, v27, v26
	s_waitcnt lgkmcnt(4)
	v_mul_f32_e32 v27, v249, v16
	v_mul_f32_e32 v28, v251, v15
	v_fmac_f32_e32 v27, v248, v14
	v_fmac_f32_e32 v28, v250, v13
	v_add_f32_e32 v26, v35, v26
	v_add_f32_e32 v27, v27, v28
	v_add_f32_e32 v35, v26, v27
	v_mul_f32_e64 v26, |v35|, s64
	v_exp_f32_e32 v30, v26
	ds_read_b128 v[236:239], v63 offset:576
	v_fmac_f32_e32 v25, 0xbf317218, v34
	v_min_f32_e32 v35, 0, v35
	v_add_f32_e32 v30, 1.0, v30
	v_log_f32_e32 v34, v30
	ds_read_b128 v[240:243], v63 offset:592
	s_waitcnt lgkmcnt(5)
	v_mul_f32_e32 v27, v221, v2
	v_fmac_f32_e32 v27, v220, v17
	v_mul_f32_e32 v26, v223, v12
	v_fmac_f32_e32 v26, v222, v10
	v_add_f32_e32 v26, v27, v26
	s_waitcnt lgkmcnt(4)
	v_mul_f32_e32 v31, v225, v11
	v_add_f32_e32 v36, v18, v26
	v_fmac_f32_e32 v31, v224, v8
	v_mul_f32_e32 v30, v227, v9
	ds_read_b128 v[244:247], v63 offset:608
	v_fmac_f32_e32 v30, v226, v7
	v_add_f32_e32 v30, v31, v30
	v_add_f32_e32 v36, v36, v30
	ds_read_b128 v[248:251], v63 offset:624
	s_waitcnt lgkmcnt(5)
	v_mul_f32_e32 v27, v229, v4
	v_fmac_f32_e32 v27, v228, v3
	v_mul_f32_e32 v26, v231, v6
	v_fmac_f32_e32 v26, v230, v5
	v_add_f32_e32 v26, v27, v26
	s_waitcnt lgkmcnt(4)
	v_mul_f32_e32 v27, v233, v16
	v_mul_f32_e32 v28, v235, v15
	v_fmac_f32_e32 v27, v232, v14
	v_fmac_f32_e32 v28, v234, v13
	v_add_f32_e32 v26, v36, v26
	v_add_f32_e32 v27, v27, v28
	v_add_f32_e32 v36, v26, v27
	v_mul_f32_e64 v26, |v36|, s64
	v_exp_f32_e32 v30, v26
	ds_read_b128 v[220:223], v63 offset:640
	v_fmac_f32_e32 v35, 0xbf317218, v34
	v_fmamk_f32 v25, v25, 0x3d800000, v24
	v_add_f32_e32 v30, 1.0, v30
	v_log_f32_e32 v34, v30
	ds_read_b128 v[224:227], v63 offset:656
	s_waitcnt lgkmcnt(5)
	v_mul_f32_e32 v27, v237, v2
	v_fmac_f32_e32 v27, v236, v17
	v_mul_f32_e32 v26, v239, v12
	v_fmac_f32_e32 v26, v238, v10
	v_add_f32_e32 v26, v27, v26
	s_waitcnt lgkmcnt(4)
	v_mul_f32_e32 v31, v241, v11
	v_add_f32_e32 v37, v18, v26
	v_fmac_f32_e32 v31, v240, v8
	v_mul_f32_e32 v30, v243, v9
	ds_read_b128 v[228:231], v63 offset:672
	v_fmac_f32_e32 v30, v242, v7
	v_add_f32_e32 v30, v31, v30
	v_add_f32_e32 v37, v37, v30
	ds_read_b128 v[232:235], v63 offset:688
	s_waitcnt lgkmcnt(5)
	v_mul_f32_e32 v27, v245, v4
	v_fmac_f32_e32 v27, v244, v3
	v_mul_f32_e32 v26, v247, v6
	v_fmac_f32_e32 v26, v246, v5
	v_add_f32_e32 v26, v27, v26
	s_waitcnt lgkmcnt(4)
	v_mul_f32_e32 v27, v249, v16
	v_mul_f32_e32 v28, v251, v15
	v_fmac_f32_e32 v27, v248, v14
	v_fmac_f32_e32 v28, v250, v13
	v_add_f32_e32 v26, v37, v26
	v_add_f32_e32 v27, v27, v28
	v_add_f32_e32 v32, v26, v27
	v_mul_f32_e64 v26, |v32|, s64
	v_exp_f32_e32 v27, v26
	v_min_f32_e32 v33, 0, v36
	v_fmac_f32_e32 v33, 0xbf317218, v34
	ds_read_b128 v[236:239], v63 offset:704
	v_add_f32_e32 v27, 1.0, v27
	v_log_f32_e32 v34, v27
	v_fmamk_f32 v26, v35, 0x3d800000, v25
	v_min_f32_e32 v36, 0, v32
	v_fmamk_f32 v27, v33, 0x3d800000, v26
	v_fmac_f32_e32 v36, 0xbf317218, v34
	ds_read_b128 v[240:243], v63 offset:720
	s_waitcnt lgkmcnt(5)
	v_mul_f32_e32 v29, v221, v2
	v_fmac_f32_e32 v29, v220, v17
	v_mul_f32_e32 v28, v223, v12
	v_fmac_f32_e32 v28, v222, v10
	v_add_f32_e32 v28, v29, v28
	s_waitcnt lgkmcnt(4)
	v_mul_f32_e32 v33, v225, v11
	v_add_f32_e32 v37, v18, v28
	v_fmac_f32_e32 v33, v224, v8
	v_mul_f32_e32 v32, v227, v9
	ds_read_b128 v[244:247], v63 offset:736
	v_fmac_f32_e32 v32, v226, v7
	v_add_f32_e32 v32, v33, v32
	v_add_f32_e32 v37, v37, v32
	ds_read_b128 v[248:251], v63 offset:752
	s_waitcnt lgkmcnt(5)
	v_mul_f32_e32 v29, v229, v4
	v_fmac_f32_e32 v29, v228, v3
	v_mul_f32_e32 v28, v231, v6
	v_fmac_f32_e32 v28, v230, v5
	v_add_f32_e32 v28, v29, v28
	s_waitcnt lgkmcnt(4)
	v_mul_f32_e32 v29, v233, v16
	v_mul_f32_e32 v30, v235, v15
	v_fmac_f32_e32 v29, v232, v14
	v_fmac_f32_e32 v30, v234, v13
	v_add_f32_e32 v28, v37, v28
	v_add_f32_e32 v29, v29, v30
	v_add_f32_e32 v29, v28, v29
	v_mul_f32_e64 v28, |v29|, s64
	v_exp_f32_e32 v34, v28
	ds_read_b128 v[220:223], v63 offset:768
	v_fmamk_f32 v28, v36, 0x3d800000, v27
	v_min_f32_e32 v29, 0, v29
	v_add_f32_e32 v34, 1.0, v34
	v_log_f32_e32 v38, v34
	ds_read_b128 v[224:227], v63 offset:784
	s_waitcnt lgkmcnt(5)
	v_mul_f32_e32 v31, v237, v2
	v_fmac_f32_e32 v31, v236, v17
	v_mul_f32_e32 v30, v239, v12
	v_fmac_f32_e32 v30, v238, v10
	v_add_f32_e32 v30, v31, v30
	s_waitcnt lgkmcnt(4)
	v_mul_f32_e32 v35, v241, v11
	v_add_f32_e32 v39, v18, v30
	v_fmac_f32_e32 v35, v240, v8
	v_mul_f32_e32 v34, v243, v9
	ds_read_b128 v[228:231], v63 offset:800
	v_fmac_f32_e32 v34, v242, v7
	v_add_f32_e32 v34, v35, v34
	v_add_f32_e32 v39, v39, v34
	ds_read_b128 v[232:235], v63 offset:816
	s_waitcnt lgkmcnt(5)
	v_mul_f32_e32 v31, v245, v4
	v_fmac_f32_e32 v31, v244, v3
	v_mul_f32_e32 v30, v247, v6
	v_fmac_f32_e32 v30, v246, v5
	v_add_f32_e32 v30, v31, v30
	s_waitcnt lgkmcnt(4)
	v_mul_f32_e32 v31, v249, v16
	v_mul_f32_e32 v32, v251, v15
	v_fmac_f32_e32 v31, v248, v14
	v_fmac_f32_e32 v32, v250, v13
	v_add_f32_e32 v30, v39, v30
	v_add_f32_e32 v31, v31, v32
	v_add_f32_e32 v39, v30, v31
	v_mul_f32_e64 v30, |v39|, s64
	v_exp_f32_e32 v34, v30
	ds_read_b128 v[236:239], v63 offset:832
	v_fmac_f32_e32 v29, 0xbf317218, v38
	v_min_f32_e32 v39, 0, v39
	v_add_f32_e32 v34, 1.0, v34
	v_log_f32_e32 v38, v34
	ds_read_b128 v[240:243], v63 offset:848
	s_waitcnt lgkmcnt(5)
	v_mul_f32_e32 v31, v221, v2
	v_fmac_f32_e32 v31, v220, v17
	v_mul_f32_e32 v30, v223, v12
	v_fmac_f32_e32 v30, v222, v10
	v_add_f32_e32 v30, v31, v30
	s_waitcnt lgkmcnt(4)
	v_mul_f32_e32 v35, v225, v11
	v_add_f32_e32 v40, v18, v30
	v_fmac_f32_e32 v35, v224, v8
	v_mul_f32_e32 v34, v227, v9
	ds_read_b128 v[244:247], v63 offset:864
	v_fmac_f32_e32 v34, v226, v7
	v_add_f32_e32 v34, v35, v34
	v_add_f32_e32 v40, v40, v34
	ds_read_b128 v[248:251], v63 offset:880
	s_waitcnt lgkmcnt(5)
	v_mul_f32_e32 v31, v229, v4
	v_fmac_f32_e32 v31, v228, v3
	v_mul_f32_e32 v30, v231, v6
	v_fmac_f32_e32 v30, v230, v5
	v_add_f32_e32 v30, v31, v30
	s_waitcnt lgkmcnt(4)
	v_mul_f32_e32 v31, v233, v16
	v_mul_f32_e32 v32, v235, v15
	v_fmac_f32_e32 v31, v232, v14
	v_fmac_f32_e32 v32, v234, v13
	v_add_f32_e32 v30, v40, v30
	v_add_f32_e32 v31, v31, v32
	v_add_f32_e32 v40, v30, v31
	v_mul_f32_e64 v30, |v40|, s64
	v_exp_f32_e32 v34, v30
	ds_read_b128 v[220:223], v63 offset:896
	v_fmac_f32_e32 v39, 0xbf317218, v38
	v_fmamk_f32 v29, v29, 0x3d800000, v28
	v_add_f32_e32 v34, 1.0, v34
	v_log_f32_e32 v38, v34
	ds_read_b128 v[224:227], v63 offset:912
	s_waitcnt lgkmcnt(5)
	v_mul_f32_e32 v31, v237, v2
	v_fmac_f32_e32 v31, v236, v17
	v_mul_f32_e32 v30, v239, v12
	v_fmac_f32_e32 v30, v238, v10
	v_add_f32_e32 v30, v31, v30
	s_waitcnt lgkmcnt(4)
	v_mul_f32_e32 v35, v241, v11
	v_add_f32_e32 v41, v18, v30
	v_fmac_f32_e32 v35, v240, v8
	v_mul_f32_e32 v34, v243, v9
	ds_read_b128 v[228:231], v63 offset:928
	v_fmac_f32_e32 v34, v242, v7
	v_add_f32_e32 v34, v35, v34
	v_add_f32_e32 v41, v41, v34
	ds_read_b128 v[232:235], v63 offset:944
	s_waitcnt lgkmcnt(5)
	v_mul_f32_e32 v31, v245, v4
	v_fmac_f32_e32 v31, v244, v3
	v_mul_f32_e32 v30, v247, v6
	v_fmac_f32_e32 v30, v246, v5
	v_add_f32_e32 v30, v31, v30
	s_waitcnt lgkmcnt(4)
	v_mul_f32_e32 v31, v249, v16
	v_mul_f32_e32 v32, v251, v15
	v_fmac_f32_e32 v31, v248, v14
	v_fmac_f32_e32 v32, v250, v13
	v_add_f32_e32 v30, v41, v30
	v_add_f32_e32 v31, v31, v32
	v_add_f32_e32 v36, v30, v31
	v_mul_f32_e64 v30, |v36|, s64
	v_exp_f32_e32 v31, v30
	v_min_f32_e32 v37, 0, v40
	v_fmac_f32_e32 v37, 0xbf317218, v38
	ds_read_b128 v[236:239], v63 offset:960
	v_add_f32_e32 v31, 1.0, v31
	v_log_f32_e32 v38, v31
	v_fmamk_f32 v30, v39, 0x3d800000, v29
	v_min_f32_e32 v40, 0, v36
	v_fmamk_f32 v31, v37, 0x3d800000, v30
	v_fmac_f32_e32 v40, 0xbf317218, v38
	ds_read_b128 v[240:243], v63 offset:976
	s_waitcnt lgkmcnt(5)
	v_mul_f32_e32 v33, v221, v2
	v_fmac_f32_e32 v33, v220, v17
	v_mul_f32_e32 v32, v223, v12
	v_fmac_f32_e32 v32, v222, v10
	v_add_f32_e32 v32, v33, v32
	s_waitcnt lgkmcnt(4)
	v_mul_f32_e32 v37, v225, v11
	v_add_f32_e32 v41, v18, v32
	v_fmac_f32_e32 v37, v224, v8
	v_mul_f32_e32 v36, v227, v9
	ds_read_b128 v[244:247], v63 offset:992
	v_fmac_f32_e32 v36, v226, v7
	v_add_f32_e32 v36, v37, v36
	v_add_f32_e32 v41, v41, v36
	ds_read_b128 v[248:251], v63 offset:1008
	s_waitcnt lgkmcnt(5)
	v_mul_f32_e32 v33, v229, v4
	v_fmac_f32_e32 v33, v228, v3
	v_mul_f32_e32 v32, v231, v6
	v_fmac_f32_e32 v32, v230, v5
	v_add_f32_e32 v32, v33, v32
	s_waitcnt lgkmcnt(4)
	v_mul_f32_e32 v33, v233, v16
	v_mul_f32_e32 v34, v235, v15
	v_fmac_f32_e32 v33, v232, v14
	v_fmac_f32_e32 v34, v234, v13
	v_add_f32_e32 v32, v41, v32
	v_add_f32_e32 v33, v33, v34
	v_add_f32_e32 v33, v32, v33
	v_mul_f32_e64 v32, |v33|, s64
	v_exp_f32_e32 v38, v32
	ds_read_b128 v[220:223], v63 offset:1024
	v_fmamk_f32 v32, v40, 0x3d800000, v31
	v_min_f32_e32 v33, 0, v33
	v_add_f32_e32 v38, 1.0, v38
	v_log_f32_e32 v42, v38
	ds_read_b128 v[224:227], v63 offset:1040
	s_waitcnt lgkmcnt(5)
	v_mul_f32_e32 v35, v237, v2
	v_fmac_f32_e32 v35, v236, v17
	v_mul_f32_e32 v34, v239, v12
	v_fmac_f32_e32 v34, v238, v10
	v_add_f32_e32 v34, v35, v34
	s_waitcnt lgkmcnt(4)
	v_mul_f32_e32 v39, v241, v11
	v_add_f32_e32 v43, v18, v34
	v_fmac_f32_e32 v39, v240, v8
	v_mul_f32_e32 v38, v243, v9
	ds_read_b128 v[228:231], v63 offset:1056
	v_fmac_f32_e32 v38, v242, v7
	v_add_f32_e32 v38, v39, v38
	v_add_f32_e32 v43, v43, v38
	ds_read_b128 v[232:235], v63 offset:1072
	s_waitcnt lgkmcnt(5)
	v_mul_f32_e32 v35, v245, v4
	v_fmac_f32_e32 v35, v244, v3
	v_mul_f32_e32 v34, v247, v6
	v_fmac_f32_e32 v34, v246, v5
	v_add_f32_e32 v34, v35, v34
	s_waitcnt lgkmcnt(4)
	v_mul_f32_e32 v35, v249, v16
	v_mul_f32_e32 v36, v251, v15
	v_fmac_f32_e32 v35, v248, v14
	v_fmac_f32_e32 v36, v250, v13
	v_add_f32_e32 v34, v43, v34
	v_add_f32_e32 v35, v35, v36
	v_add_f32_e32 v43, v34, v35
	v_mul_f32_e64 v34, |v43|, s64
	v_exp_f32_e32 v38, v34
	ds_read_b128 v[236:239], v63 offset:1088
	v_fmac_f32_e32 v33, 0xbf317218, v42
	v_min_f32_e32 v43, 0, v43
	v_add_f32_e32 v38, 1.0, v38
	v_log_f32_e32 v42, v38
	ds_read_b128 v[240:243], v63 offset:1104
	s_waitcnt lgkmcnt(5)
	v_mul_f32_e32 v35, v221, v2
	v_fmac_f32_e32 v35, v220, v17
	v_mul_f32_e32 v34, v223, v12
	v_fmac_f32_e32 v34, v222, v10
	v_add_f32_e32 v34, v35, v34
	s_waitcnt lgkmcnt(4)
	v_mul_f32_e32 v39, v225, v11
	v_add_f32_e32 v44, v18, v34
	v_fmac_f32_e32 v39, v224, v8
	v_mul_f32_e32 v38, v227, v9
	ds_read_b128 v[244:247], v63 offset:1120
	v_fmac_f32_e32 v38, v226, v7
	v_add_f32_e32 v38, v39, v38
	v_add_f32_e32 v44, v44, v38
	ds_read_b128 v[248:251], v63 offset:1136
	s_waitcnt lgkmcnt(5)
	v_mul_f32_e32 v35, v229, v4
	v_fmac_f32_e32 v35, v228, v3
	v_mul_f32_e32 v34, v231, v6
	v_fmac_f32_e32 v34, v230, v5
	v_add_f32_e32 v34, v35, v34
	s_waitcnt lgkmcnt(4)
	v_mul_f32_e32 v35, v233, v16
	v_mul_f32_e32 v36, v235, v15
	v_fmac_f32_e32 v35, v232, v14
	v_fmac_f32_e32 v36, v234, v13
	v_add_f32_e32 v34, v44, v34
	v_add_f32_e32 v35, v35, v36
	v_add_f32_e32 v44, v34, v35
	v_mul_f32_e64 v34, |v44|, s64
	v_exp_f32_e32 v38, v34
	ds_read_b128 v[220:223], v63 offset:1152
	v_fmac_f32_e32 v43, 0xbf317218, v42
	v_fmamk_f32 v33, v33, 0x3d800000, v32
	v_add_f32_e32 v38, 1.0, v38
	v_log_f32_e32 v42, v38
	ds_read_b128 v[224:227], v63 offset:1168
	s_waitcnt lgkmcnt(5)
	v_mul_f32_e32 v35, v237, v2
	v_fmac_f32_e32 v35, v236, v17
	v_mul_f32_e32 v34, v239, v12
	v_fmac_f32_e32 v34, v238, v10
	v_add_f32_e32 v34, v35, v34
	s_waitcnt lgkmcnt(4)
	v_mul_f32_e32 v39, v241, v11
	v_add_f32_e32 v45, v18, v34
	v_fmac_f32_e32 v39, v240, v8
	v_mul_f32_e32 v38, v243, v9
	ds_read_b128 v[228:231], v63 offset:1184
	v_fmac_f32_e32 v38, v242, v7
	v_add_f32_e32 v38, v39, v38
	v_add_f32_e32 v45, v45, v38
	ds_read_b128 v[232:235], v63 offset:1200
	s_waitcnt lgkmcnt(5)
	v_mul_f32_e32 v35, v245, v4
	v_fmac_f32_e32 v35, v244, v3
	v_mul_f32_e32 v34, v247, v6
	v_fmac_f32_e32 v34, v246, v5
	v_add_f32_e32 v34, v35, v34
	s_waitcnt lgkmcnt(4)
	v_mul_f32_e32 v35, v249, v16
	v_mul_f32_e32 v36, v251, v15
	v_fmac_f32_e32 v35, v248, v14
	v_fmac_f32_e32 v36, v250, v13
	v_add_f32_e32 v34, v45, v34
	v_add_f32_e32 v35, v35, v36
	v_add_f32_e32 v40, v34, v35
	v_mul_f32_e64 v34, |v40|, s64
	v_exp_f32_e32 v35, v34
	v_min_f32_e32 v41, 0, v44
	v_fmac_f32_e32 v41, 0xbf317218, v42
	ds_read_b128 v[236:239], v63 offset:1216
	v_add_f32_e32 v35, 1.0, v35
	v_log_f32_e32 v42, v35
	v_fmamk_f32 v34, v43, 0x3d800000, v33
	v_min_f32_e32 v44, 0, v40
	v_fmamk_f32 v35, v41, 0x3d800000, v34
	v_fmac_f32_e32 v44, 0xbf317218, v42
	ds_read_b128 v[240:243], v63 offset:1232
	s_waitcnt lgkmcnt(5)
	v_mul_f32_e32 v37, v221, v2
	v_fmac_f32_e32 v37, v220, v17
	v_mul_f32_e32 v36, v223, v12
	v_fmac_f32_e32 v36, v222, v10
	v_add_f32_e32 v36, v37, v36
	s_waitcnt lgkmcnt(4)
	v_mul_f32_e32 v41, v225, v11
	v_add_f32_e32 v45, v18, v36
	v_fmac_f32_e32 v41, v224, v8
	v_mul_f32_e32 v40, v227, v9
	ds_read_b128 v[244:247], v63 offset:1248
	v_fmac_f32_e32 v40, v226, v7
	v_add_f32_e32 v40, v41, v40
	v_add_f32_e32 v45, v45, v40
	ds_read_b128 v[248:251], v63 offset:1264
	s_waitcnt lgkmcnt(5)
	v_mul_f32_e32 v37, v229, v4
	v_fmac_f32_e32 v37, v228, v3
	v_mul_f32_e32 v36, v231, v6
	v_fmac_f32_e32 v36, v230, v5
	v_add_f32_e32 v36, v37, v36
	s_waitcnt lgkmcnt(4)
	v_mul_f32_e32 v37, v233, v16
	v_mul_f32_e32 v38, v235, v15
	v_fmac_f32_e32 v37, v232, v14
	v_fmac_f32_e32 v38, v234, v13
	v_add_f32_e32 v36, v45, v36
	v_add_f32_e32 v37, v37, v38
	v_add_f32_e32 v37, v36, v37
	v_mul_f32_e64 v36, |v37|, s64
	v_exp_f32_e32 v42, v36
	ds_read_b128 v[220:223], v63 offset:1280
	v_fmamk_f32 v36, v44, 0x3d800000, v35
	v_min_f32_e32 v37, 0, v37
	v_add_f32_e32 v42, 1.0, v42
	v_log_f32_e32 v46, v42
	ds_read_b128 v[224:227], v63 offset:1296
	s_waitcnt lgkmcnt(5)
	v_mul_f32_e32 v39, v237, v2
	v_fmac_f32_e32 v39, v236, v17
	v_mul_f32_e32 v38, v239, v12
	v_fmac_f32_e32 v38, v238, v10
	v_add_f32_e32 v38, v39, v38
	s_waitcnt lgkmcnt(4)
	v_mul_f32_e32 v43, v241, v11
	v_add_f32_e32 v47, v18, v38
	v_fmac_f32_e32 v43, v240, v8
	v_mul_f32_e32 v42, v243, v9
	ds_read_b128 v[228:231], v63 offset:1312
	v_fmac_f32_e32 v42, v242, v7
	v_add_f32_e32 v42, v43, v42
	v_add_f32_e32 v47, v47, v42
	ds_read_b128 v[232:235], v63 offset:1328
	s_waitcnt lgkmcnt(5)
	v_mul_f32_e32 v39, v245, v4
	v_fmac_f32_e32 v39, v244, v3
	v_mul_f32_e32 v38, v247, v6
	v_fmac_f32_e32 v38, v246, v5
	v_add_f32_e32 v38, v39, v38
	s_waitcnt lgkmcnt(4)
	v_mul_f32_e32 v39, v249, v16
	v_mul_f32_e32 v40, v251, v15
	v_fmac_f32_e32 v39, v248, v14
	v_fmac_f32_e32 v40, v250, v13
	v_add_f32_e32 v38, v47, v38
	v_add_f32_e32 v39, v39, v40
	v_add_f32_e32 v47, v38, v39
	v_mul_f32_e64 v38, |v47|, s64
	v_exp_f32_e32 v42, v38
	ds_read_b128 v[236:239], v63 offset:1344
	v_fmac_f32_e32 v37, 0xbf317218, v46
	v_min_f32_e32 v47, 0, v47
	v_add_f32_e32 v42, 1.0, v42
	v_log_f32_e32 v46, v42
	ds_read_b128 v[240:243], v63 offset:1360
	s_waitcnt lgkmcnt(5)
	v_mul_f32_e32 v39, v221, v2
	v_fmac_f32_e32 v39, v220, v17
	v_mul_f32_e32 v38, v223, v12
	v_fmac_f32_e32 v38, v222, v10
	v_add_f32_e32 v38, v39, v38
	s_waitcnt lgkmcnt(4)
	v_mul_f32_e32 v43, v225, v11
	v_add_f32_e32 v48, v18, v38
	v_fmac_f32_e32 v43, v224, v8
	v_mul_f32_e32 v42, v227, v9
	ds_read_b128 v[244:247], v63 offset:1376
	v_fmac_f32_e32 v42, v226, v7
	v_add_f32_e32 v42, v43, v42
	v_add_f32_e32 v48, v48, v42
	ds_read_b128 v[248:251], v63 offset:1392
	s_waitcnt lgkmcnt(5)
	v_mul_f32_e32 v39, v229, v4
	v_fmac_f32_e32 v39, v228, v3
	v_mul_f32_e32 v38, v231, v6
	v_fmac_f32_e32 v38, v230, v5
	v_add_f32_e32 v38, v39, v38
	s_waitcnt lgkmcnt(4)
	v_mul_f32_e32 v39, v233, v16
	v_mul_f32_e32 v40, v235, v15
	v_fmac_f32_e32 v39, v232, v14
	v_fmac_f32_e32 v40, v234, v13
	v_add_f32_e32 v38, v48, v38
	v_add_f32_e32 v39, v39, v40
	v_add_f32_e32 v48, v38, v39
	v_mul_f32_e64 v38, |v48|, s64
	v_exp_f32_e32 v42, v38
	ds_read_b128 v[220:223], v63 offset:1408
	v_fmac_f32_e32 v47, 0xbf317218, v46
	v_fmamk_f32 v37, v37, 0x3d800000, v36
	v_add_f32_e32 v42, 1.0, v42
	v_log_f32_e32 v46, v42
	ds_read_b128 v[224:227], v63 offset:1424
	s_waitcnt lgkmcnt(5)
	v_mul_f32_e32 v39, v237, v2
	v_fmac_f32_e32 v39, v236, v17
	v_mul_f32_e32 v38, v239, v12
	v_fmac_f32_e32 v38, v238, v10
	v_add_f32_e32 v38, v39, v38
	s_waitcnt lgkmcnt(4)
	v_mul_f32_e32 v43, v241, v11
	v_add_f32_e32 v49, v18, v38
	v_fmac_f32_e32 v43, v240, v8
	v_mul_f32_e32 v42, v243, v9
	ds_read_b128 v[228:231], v63 offset:1440
	v_fmac_f32_e32 v42, v242, v7
	v_add_f32_e32 v42, v43, v42
	v_add_f32_e32 v49, v49, v42
	ds_read_b128 v[232:235], v63 offset:1456
	s_waitcnt lgkmcnt(5)
	v_mul_f32_e32 v39, v245, v4
	v_fmac_f32_e32 v39, v244, v3
	v_mul_f32_e32 v38, v247, v6
	v_fmac_f32_e32 v38, v246, v5
	v_add_f32_e32 v38, v39, v38
	s_waitcnt lgkmcnt(4)
	v_mul_f32_e32 v39, v249, v16
	v_mul_f32_e32 v40, v251, v15
	v_fmac_f32_e32 v39, v248, v14
	v_fmac_f32_e32 v40, v250, v13
	v_add_f32_e32 v38, v49, v38
	v_add_f32_e32 v39, v39, v40
	v_add_f32_e32 v44, v38, v39
	v_mul_f32_e64 v38, |v44|, s64
	v_exp_f32_e32 v39, v38
	v_min_f32_e32 v45, 0, v48
	v_fmac_f32_e32 v45, 0xbf317218, v46
	ds_read_b128 v[236:239], v63 offset:1472
	v_add_f32_e32 v39, 1.0, v39
	v_log_f32_e32 v46, v39
	v_fmamk_f32 v38, v47, 0x3d800000, v37
	v_min_f32_e32 v48, 0, v44
	v_fmamk_f32 v39, v45, 0x3d800000, v38
	v_fmac_f32_e32 v48, 0xbf317218, v46
	ds_read_b128 v[240:243], v63 offset:1488
	s_waitcnt lgkmcnt(5)
	v_mul_f32_e32 v41, v221, v2
	v_fmac_f32_e32 v41, v220, v17
	v_mul_f32_e32 v40, v223, v12
	v_fmac_f32_e32 v40, v222, v10
	v_add_f32_e32 v40, v41, v40
	s_waitcnt lgkmcnt(4)
	v_mul_f32_e32 v45, v225, v11
	v_add_f32_e32 v49, v18, v40
	v_fmac_f32_e32 v45, v224, v8
	v_mul_f32_e32 v44, v227, v9
	ds_read_b128 v[244:247], v63 offset:1504
	v_fmac_f32_e32 v44, v226, v7
	v_add_f32_e32 v44, v45, v44
	v_add_f32_e32 v49, v49, v44
	ds_read_b128 v[248:251], v63 offset:1520
	s_waitcnt lgkmcnt(5)
	v_mul_f32_e32 v41, v229, v4
	v_fmac_f32_e32 v41, v228, v3
	v_mul_f32_e32 v40, v231, v6
	v_fmac_f32_e32 v40, v230, v5
	v_add_f32_e32 v40, v41, v40
	s_waitcnt lgkmcnt(4)
	v_mul_f32_e32 v41, v233, v16
	v_mul_f32_e32 v42, v235, v15
	v_fmac_f32_e32 v41, v232, v14
	v_fmac_f32_e32 v42, v234, v13
	v_add_f32_e32 v40, v49, v40
	v_add_f32_e32 v41, v41, v42
	v_add_f32_e32 v41, v40, v41
	v_mul_f32_e64 v40, |v41|, s64
	v_exp_f32_e32 v46, v40
	ds_read_b128 v[220:223], v63 offset:1536
	v_fmamk_f32 v40, v48, 0x3d800000, v39
	v_min_f32_e32 v41, 0, v41
	v_add_f32_e32 v46, 1.0, v46
	v_log_f32_e32 v50, v46
	ds_read_b128 v[224:227], v63 offset:1552
	s_waitcnt lgkmcnt(5)
	v_mul_f32_e32 v43, v237, v2
	v_fmac_f32_e32 v43, v236, v17
	v_mul_f32_e32 v42, v239, v12
	v_fmac_f32_e32 v42, v238, v10
	v_add_f32_e32 v42, v43, v42
	s_waitcnt lgkmcnt(4)
	v_mul_f32_e32 v47, v241, v11
	v_add_f32_e32 v51, v18, v42
	v_fmac_f32_e32 v47, v240, v8
	v_mul_f32_e32 v46, v243, v9
	ds_read_b128 v[228:231], v63 offset:1568
	v_fmac_f32_e32 v46, v242, v7
	v_add_f32_e32 v46, v47, v46
	v_add_f32_e32 v51, v51, v46
	ds_read_b128 v[232:235], v63 offset:1584
	s_waitcnt lgkmcnt(5)
	v_mul_f32_e32 v43, v245, v4
	v_fmac_f32_e32 v43, v244, v3
	v_mul_f32_e32 v42, v247, v6
	v_fmac_f32_e32 v42, v246, v5
	v_add_f32_e32 v42, v43, v42
	s_waitcnt lgkmcnt(4)
	v_mul_f32_e32 v43, v249, v16
	v_mul_f32_e32 v44, v251, v15
	v_fmac_f32_e32 v43, v248, v14
	v_fmac_f32_e32 v44, v250, v13
	v_add_f32_e32 v42, v51, v42
	v_add_f32_e32 v43, v43, v44
	v_add_f32_e32 v51, v42, v43
	v_mul_f32_e64 v42, |v51|, s64
	v_exp_f32_e32 v46, v42
	ds_read_b128 v[236:239], v63 offset:1600
	v_fmac_f32_e32 v41, 0xbf317218, v50
	v_min_f32_e32 v51, 0, v51
	v_add_f32_e32 v46, 1.0, v46
	v_log_f32_e32 v50, v46
	ds_read_b128 v[240:243], v63 offset:1616
	s_waitcnt lgkmcnt(5)
	v_mul_f32_e32 v43, v221, v2
	v_fmac_f32_e32 v43, v220, v17
	v_mul_f32_e32 v42, v223, v12
	v_fmac_f32_e32 v42, v222, v10
	v_add_f32_e32 v42, v43, v42
	s_waitcnt lgkmcnt(4)
	v_mul_f32_e32 v47, v225, v11
	v_add_f32_e32 v52, v18, v42
	v_fmac_f32_e32 v47, v224, v8
	v_mul_f32_e32 v46, v227, v9
	ds_read_b128 v[244:247], v63 offset:1632
	v_fmac_f32_e32 v46, v226, v7
	v_add_f32_e32 v46, v47, v46
	v_add_f32_e32 v52, v52, v46
	ds_read_b128 v[248:251], v63 offset:1648
	s_waitcnt lgkmcnt(5)
	v_mul_f32_e32 v43, v229, v4
	v_fmac_f32_e32 v43, v228, v3
	v_mul_f32_e32 v42, v231, v6
	v_fmac_f32_e32 v42, v230, v5
	v_add_f32_e32 v42, v43, v42
	s_waitcnt lgkmcnt(4)
	v_mul_f32_e32 v43, v233, v16
	v_mul_f32_e32 v44, v235, v15
	v_fmac_f32_e32 v43, v232, v14
	v_fmac_f32_e32 v44, v234, v13
	v_add_f32_e32 v42, v52, v42
	v_add_f32_e32 v43, v43, v44
	v_add_f32_e32 v52, v42, v43
	v_mul_f32_e64 v42, |v52|, s64
	v_exp_f32_e32 v46, v42
	ds_read_b128 v[220:223], v63 offset:1664
	v_fmac_f32_e32 v51, 0xbf317218, v50
	v_fmamk_f32 v41, v41, 0x3d800000, v40
	v_add_f32_e32 v46, 1.0, v46
	v_log_f32_e32 v50, v46
	ds_read_b128 v[224:227], v63 offset:1680
	s_waitcnt lgkmcnt(5)
	v_mul_f32_e32 v43, v237, v2
	v_fmac_f32_e32 v43, v236, v17
	v_mul_f32_e32 v42, v239, v12
	v_fmac_f32_e32 v42, v238, v10
	v_add_f32_e32 v42, v43, v42
	s_waitcnt lgkmcnt(4)
	v_mul_f32_e32 v47, v241, v11
	v_add_f32_e32 v53, v18, v42
	v_fmac_f32_e32 v47, v240, v8
	v_mul_f32_e32 v46, v243, v9
	ds_read_b128 v[228:231], v63 offset:1696
	v_fmac_f32_e32 v46, v242, v7
	v_add_f32_e32 v46, v47, v46
	v_add_f32_e32 v53, v53, v46
	ds_read_b128 v[232:235], v63 offset:1712
	s_waitcnt lgkmcnt(5)
	v_mul_f32_e32 v43, v245, v4
	v_fmac_f32_e32 v43, v244, v3
	v_mul_f32_e32 v42, v247, v6
	v_fmac_f32_e32 v42, v246, v5
	v_add_f32_e32 v42, v43, v42
	s_waitcnt lgkmcnt(4)
	v_mul_f32_e32 v43, v249, v16
	v_mul_f32_e32 v44, v251, v15
	v_fmac_f32_e32 v43, v248, v14
	v_fmac_f32_e32 v44, v250, v13
	v_add_f32_e32 v42, v53, v42
	v_add_f32_e32 v43, v43, v44
	v_add_f32_e32 v48, v42, v43
	v_mul_f32_e64 v42, |v48|, s64
	v_exp_f32_e32 v43, v42
	v_min_f32_e32 v49, 0, v52
	v_fmac_f32_e32 v49, 0xbf317218, v50
	ds_read_b128 v[236:239], v63 offset:1728
	v_add_f32_e32 v43, 1.0, v43
	v_log_f32_e32 v50, v43
	v_fmamk_f32 v42, v51, 0x3d800000, v41
	v_min_f32_e32 v52, 0, v48
	v_fmamk_f32 v43, v49, 0x3d800000, v42
	v_fmac_f32_e32 v52, 0xbf317218, v50
	ds_read_b128 v[240:243], v63 offset:1744
	s_waitcnt lgkmcnt(5)
	v_mul_f32_e32 v45, v221, v2
	v_fmac_f32_e32 v45, v220, v17
	v_mul_f32_e32 v44, v223, v12
	v_fmac_f32_e32 v44, v222, v10
	v_add_f32_e32 v44, v45, v44
	s_waitcnt lgkmcnt(4)
	v_mul_f32_e32 v49, v225, v11
	v_add_f32_e32 v53, v18, v44
	v_fmac_f32_e32 v49, v224, v8
	v_mul_f32_e32 v48, v227, v9
	ds_read_b128 v[244:247], v63 offset:1760
	v_fmac_f32_e32 v48, v226, v7
	v_add_f32_e32 v48, v49, v48
	v_add_f32_e32 v53, v53, v48
	ds_read_b128 v[248:251], v63 offset:1776
	s_waitcnt lgkmcnt(5)
	v_mul_f32_e32 v45, v229, v4
	v_fmac_f32_e32 v45, v228, v3
	v_mul_f32_e32 v44, v231, v6
	v_fmac_f32_e32 v44, v230, v5
	v_add_f32_e32 v44, v45, v44
	s_waitcnt lgkmcnt(4)
	v_mul_f32_e32 v45, v233, v16
	v_mul_f32_e32 v46, v235, v15
	v_fmac_f32_e32 v45, v232, v14
	v_fmac_f32_e32 v46, v234, v13
	v_add_f32_e32 v44, v53, v44
	v_add_f32_e32 v45, v45, v46
	v_add_f32_e32 v45, v44, v45
	v_mul_f32_e64 v44, |v45|, s64
	v_exp_f32_e32 v50, v44
	ds_read_b128 v[220:223], v63 offset:1792
	v_fmamk_f32 v44, v52, 0x3d800000, v43
	v_min_f32_e32 v45, 0, v45
	v_add_f32_e32 v50, 1.0, v50
	v_log_f32_e32 v54, v50
	ds_read_b128 v[224:227], v63 offset:1808
	s_waitcnt lgkmcnt(5)
	v_mul_f32_e32 v47, v237, v2
	v_fmac_f32_e32 v47, v236, v17
	v_mul_f32_e32 v46, v239, v12
	v_fmac_f32_e32 v46, v238, v10
	v_add_f32_e32 v46, v47, v46
	s_waitcnt lgkmcnt(4)
	v_mul_f32_e32 v51, v241, v11
	v_add_f32_e32 v55, v18, v46
	v_fmac_f32_e32 v51, v240, v8
	v_mul_f32_e32 v50, v243, v9
	ds_read_b128 v[228:231], v63 offset:1824
	v_fmac_f32_e32 v50, v242, v7
	v_add_f32_e32 v50, v51, v50
	v_add_f32_e32 v55, v55, v50
	ds_read_b128 v[232:235], v63 offset:1840
	s_waitcnt lgkmcnt(5)
	v_mul_f32_e32 v47, v245, v4
	v_fmac_f32_e32 v47, v244, v3
	v_mul_f32_e32 v46, v247, v6
	v_fmac_f32_e32 v46, v246, v5
	v_add_f32_e32 v46, v47, v46
	s_waitcnt lgkmcnt(4)
	v_mul_f32_e32 v47, v249, v16
	v_mul_f32_e32 v48, v251, v15
	v_fmac_f32_e32 v47, v248, v14
	v_fmac_f32_e32 v48, v250, v13
	v_add_f32_e32 v46, v55, v46
	v_add_f32_e32 v47, v47, v48
	v_add_f32_e32 v55, v46, v47
	v_mul_f32_e64 v46, |v55|, s64
	v_exp_f32_e32 v50, v46
	ds_read_b128 v[236:239], v63 offset:1856
	v_fmac_f32_e32 v45, 0xbf317218, v54
	v_min_f32_e32 v55, 0, v55
	v_add_f32_e32 v50, 1.0, v50
	v_log_f32_e32 v54, v50
	ds_read_b128 v[240:243], v63 offset:1872
	s_waitcnt lgkmcnt(5)
	v_mul_f32_e32 v47, v221, v2
	v_fmac_f32_e32 v47, v220, v17
	v_mul_f32_e32 v46, v223, v12
	v_fmac_f32_e32 v46, v222, v10
	v_add_f32_e32 v46, v47, v46
	s_waitcnt lgkmcnt(4)
	v_mul_f32_e32 v51, v225, v11
	v_add_f32_e32 v56, v18, v46
	v_fmac_f32_e32 v51, v224, v8
	v_mul_f32_e32 v50, v227, v9
	ds_read_b128 v[244:247], v63 offset:1888
	v_fmac_f32_e32 v50, v226, v7
	v_add_f32_e32 v50, v51, v50
	v_add_f32_e32 v56, v56, v50
	ds_read_b128 v[248:251], v63 offset:1904
	s_waitcnt lgkmcnt(5)
	v_mul_f32_e32 v47, v229, v4
	v_fmac_f32_e32 v47, v228, v3
	v_mul_f32_e32 v46, v231, v6
	v_fmac_f32_e32 v46, v230, v5
	v_add_f32_e32 v46, v47, v46
	s_waitcnt lgkmcnt(4)
	v_mul_f32_e32 v47, v233, v16
	v_mul_f32_e32 v48, v235, v15
	v_fmac_f32_e32 v47, v232, v14
	v_fmac_f32_e32 v48, v234, v13
	v_add_f32_e32 v46, v56, v46
	v_add_f32_e32 v47, v47, v48
	v_add_f32_e32 v56, v46, v47
	v_mul_f32_e64 v46, |v56|, s64
	v_exp_f32_e32 v50, v46
	ds_read_b128 v[220:223], v63 offset:1920
	v_fmac_f32_e32 v55, 0xbf317218, v54
	v_fmamk_f32 v45, v45, 0x3d800000, v44
	v_add_f32_e32 v50, 1.0, v50
	v_log_f32_e32 v54, v50
	ds_read_b128 v[224:227], v63 offset:1936
	s_waitcnt lgkmcnt(5)
	v_mul_f32_e32 v47, v237, v2
	v_fmac_f32_e32 v47, v236, v17
	v_mul_f32_e32 v46, v239, v12
	v_fmac_f32_e32 v46, v238, v10
	v_add_f32_e32 v46, v47, v46
	s_waitcnt lgkmcnt(4)
	v_mul_f32_e32 v51, v241, v11
	v_add_f32_e32 v57, v18, v46
	v_fmac_f32_e32 v51, v240, v8
	v_mul_f32_e32 v50, v243, v9
	ds_read_b128 v[228:231], v63 offset:1952
	v_fmac_f32_e32 v50, v242, v7
	v_add_f32_e32 v50, v51, v50
	v_add_f32_e32 v57, v57, v50
	ds_read_b128 v[232:235], v63 offset:1968
	s_waitcnt lgkmcnt(5)
	v_mul_f32_e32 v47, v245, v4
	v_fmac_f32_e32 v47, v244, v3
	v_mul_f32_e32 v46, v247, v6
	v_fmac_f32_e32 v46, v246, v5
	v_add_f32_e32 v46, v47, v46
	s_waitcnt lgkmcnt(4)
	v_mul_f32_e32 v47, v249, v16
	v_mul_f32_e32 v48, v251, v15
	v_fmac_f32_e32 v47, v248, v14
	v_fmac_f32_e32 v48, v250, v13
	v_add_f32_e32 v46, v57, v46
	v_add_f32_e32 v47, v47, v48
	v_add_f32_e32 v52, v46, v47
	v_mul_f32_e64 v46, |v52|, s64
	v_exp_f32_e32 v47, v46
	v_min_f32_e32 v53, 0, v56
	v_fmac_f32_e32 v53, 0xbf317218, v54
	ds_read_b128 v[236:239], v63 offset:1984
	v_add_f32_e32 v47, 1.0, v47
	v_log_f32_e32 v54, v47
	v_fmamk_f32 v46, v55, 0x3d800000, v45
	v_min_f32_e32 v56, 0, v52
	v_fmamk_f32 v47, v53, 0x3d800000, v46
	v_fmac_f32_e32 v56, 0xbf317218, v54
	ds_read_b128 v[240:243], v63 offset:2000
	s_waitcnt lgkmcnt(5)
	v_mul_f32_e32 v49, v221, v2
	v_fmac_f32_e32 v49, v220, v17
	v_mul_f32_e32 v48, v223, v12
	v_fmac_f32_e32 v48, v222, v10
	v_add_f32_e32 v48, v49, v48
	s_waitcnt lgkmcnt(4)
	v_mul_f32_e32 v53, v225, v11
	v_add_f32_e32 v57, v18, v48
	v_fmac_f32_e32 v53, v224, v8
	v_mul_f32_e32 v52, v227, v9
	ds_read_b128 v[244:247], v63 offset:2016
	v_fmac_f32_e32 v52, v226, v7
	v_add_f32_e32 v52, v53, v52
	v_add_f32_e32 v57, v57, v52
	ds_read_b128 v[248:251], v63 offset:2032
	s_waitcnt lgkmcnt(5)
	v_mul_f32_e32 v49, v229, v4
	v_fmac_f32_e32 v49, v228, v3
	v_mul_f32_e32 v48, v231, v6
	v_fmac_f32_e32 v48, v230, v5
	v_add_f32_e32 v48, v49, v48
	s_waitcnt lgkmcnt(4)
	v_mul_f32_e32 v49, v233, v16
	v_mul_f32_e32 v50, v235, v15
	v_fmac_f32_e32 v49, v232, v14
	v_fmac_f32_e32 v50, v234, v13
	v_add_f32_e32 v48, v57, v48
	v_add_f32_e32 v49, v49, v50
	v_add_f32_e32 v49, v48, v49
	v_mul_f32_e64 v48, |v49|, s64
	v_exp_f32_e32 v54, v48
	ds_read_b128 v[220:223], v63 offset:2048
	v_fmamk_f32 v48, v56, 0x3d800000, v47
	v_min_f32_e32 v49, 0, v49
	v_add_f32_e32 v54, 1.0, v54
	v_log_f32_e32 v58, v54
	ds_read_b128 v[224:227], v63 offset:2064
	s_waitcnt lgkmcnt(5)
	v_mul_f32_e32 v51, v237, v2
	v_fmac_f32_e32 v51, v236, v17
	v_mul_f32_e32 v50, v239, v12
	v_fmac_f32_e32 v50, v238, v10
	v_add_f32_e32 v50, v51, v50
	s_waitcnt lgkmcnt(4)
	v_mul_f32_e32 v55, v241, v11
	v_add_f32_e32 v59, v18, v50
	v_fmac_f32_e32 v55, v240, v8
	v_mul_f32_e32 v54, v243, v9
	ds_read_b128 v[228:231], v63 offset:2080
	v_fmac_f32_e32 v54, v242, v7
	v_add_f32_e32 v54, v55, v54
	v_add_f32_e32 v59, v59, v54
	ds_read_b128 v[232:235], v63 offset:2096
	s_waitcnt lgkmcnt(5)
	v_mul_f32_e32 v51, v245, v4
	v_fmac_f32_e32 v51, v244, v3
	v_mul_f32_e32 v50, v247, v6
	v_fmac_f32_e32 v50, v246, v5
	v_add_f32_e32 v50, v51, v50
	s_waitcnt lgkmcnt(4)
	v_mul_f32_e32 v51, v249, v16
	v_mul_f32_e32 v52, v251, v15
	v_fmac_f32_e32 v51, v248, v14
	v_fmac_f32_e32 v52, v250, v13
	v_add_f32_e32 v50, v59, v50
	v_add_f32_e32 v51, v51, v52
	v_add_f32_e32 v59, v50, v51
	v_mul_f32_e64 v50, |v59|, s64
	v_exp_f32_e32 v54, v50
	ds_read_b128 v[236:239], v63 offset:2112
	v_fmac_f32_e32 v49, 0xbf317218, v58
	v_min_f32_e32 v59, 0, v59
	v_add_f32_e32 v54, 1.0, v54
	v_log_f32_e32 v58, v54
	ds_read_b128 v[240:243], v63 offset:2128
	s_waitcnt lgkmcnt(5)
	v_mul_f32_e32 v51, v221, v2
	v_fmac_f32_e32 v51, v220, v17
	v_mul_f32_e32 v50, v223, v12
	v_fmac_f32_e32 v50, v222, v10
	v_add_f32_e32 v50, v51, v50
	s_waitcnt lgkmcnt(4)
	v_mul_f32_e32 v55, v225, v11
	v_add_f32_e32 v60, v18, v50
	v_fmac_f32_e32 v55, v224, v8
	v_mul_f32_e32 v54, v227, v9
	ds_read_b128 v[244:247], v63 offset:2144
	v_fmac_f32_e32 v54, v226, v7
	v_add_f32_e32 v54, v55, v54
	v_add_f32_e32 v60, v60, v54
	ds_read_b128 v[248:251], v63 offset:2160
	s_waitcnt lgkmcnt(5)
	v_mul_f32_e32 v51, v229, v4
	v_fmac_f32_e32 v51, v228, v3
	v_mul_f32_e32 v50, v231, v6
	v_fmac_f32_e32 v50, v230, v5
	v_add_f32_e32 v50, v51, v50
	s_waitcnt lgkmcnt(4)
	v_mul_f32_e32 v51, v233, v16
	v_mul_f32_e32 v52, v235, v15
	v_fmac_f32_e32 v51, v232, v14
	v_fmac_f32_e32 v52, v234, v13
	v_add_f32_e32 v50, v60, v50
	v_add_f32_e32 v51, v51, v52
	v_add_f32_e32 v60, v50, v51
	v_mul_f32_e64 v50, |v60|, s64
	v_exp_f32_e32 v54, v50
	ds_read_b128 v[220:223], v63 offset:2176
	v_fmac_f32_e32 v59, 0xbf317218, v58
	v_fmamk_f32 v49, v49, 0x3d800000, v48
	v_add_f32_e32 v54, 1.0, v54
	v_log_f32_e32 v58, v54
	ds_read_b128 v[224:227], v63 offset:2192
	s_waitcnt lgkmcnt(5)
	v_mul_f32_e32 v51, v237, v2
	v_fmac_f32_e32 v51, v236, v17
	v_mul_f32_e32 v50, v239, v12
	v_fmac_f32_e32 v50, v238, v10
	v_add_f32_e32 v50, v51, v50
	s_waitcnt lgkmcnt(4)
	v_mul_f32_e32 v55, v241, v11
	v_add_f32_e32 v61, v18, v50
	v_fmac_f32_e32 v55, v240, v8
	v_mul_f32_e32 v54, v243, v9
	ds_read_b128 v[228:231], v63 offset:2208
	v_fmac_f32_e32 v54, v242, v7
	v_add_f32_e32 v54, v55, v54
	v_add_f32_e32 v61, v61, v54
	ds_read_b128 v[232:235], v63 offset:2224
	s_waitcnt lgkmcnt(5)
	v_mul_f32_e32 v51, v245, v4
	v_fmac_f32_e32 v51, v244, v3
	v_mul_f32_e32 v50, v247, v6
	v_fmac_f32_e32 v50, v246, v5
	v_add_f32_e32 v50, v51, v50
	s_waitcnt lgkmcnt(4)
	v_mul_f32_e32 v51, v249, v16
	v_mul_f32_e32 v52, v251, v15
	v_fmac_f32_e32 v51, v248, v14
	v_fmac_f32_e32 v52, v250, v13
	v_add_f32_e32 v50, v61, v50
	v_add_f32_e32 v51, v51, v52
	v_add_f32_e32 v56, v50, v51
	v_mul_f32_e64 v50, |v56|, s64
	v_exp_f32_e32 v51, v50
	v_min_f32_e32 v57, 0, v60
	v_fmac_f32_e32 v57, 0xbf317218, v58
	ds_read_b128 v[236:239], v63 offset:2240
	v_add_f32_e32 v51, 1.0, v51
	v_log_f32_e32 v58, v51
	v_fmamk_f32 v50, v59, 0x3d800000, v49
	v_min_f32_e32 v60, 0, v56
	v_fmamk_f32 v51, v57, 0x3d800000, v50
	v_fmac_f32_e32 v60, 0xbf317218, v58
	ds_read_b128 v[240:243], v63 offset:2256
	s_waitcnt lgkmcnt(5)
	v_mul_f32_e32 v53, v221, v2
	v_fmac_f32_e32 v53, v220, v17
	v_mul_f32_e32 v52, v223, v12
	v_fmac_f32_e32 v52, v222, v10
	v_add_f32_e32 v52, v53, v52
	s_waitcnt lgkmcnt(4)
	v_mul_f32_e32 v57, v225, v11
	v_add_f32_e32 v61, v18, v52
	v_fmac_f32_e32 v57, v224, v8
	v_mul_f32_e32 v56, v227, v9
	ds_read_b128 v[244:247], v63 offset:2272
	v_fmac_f32_e32 v56, v226, v7
	v_add_f32_e32 v56, v57, v56
	v_add_f32_e32 v61, v61, v56
	ds_read_b128 v[248:251], v63 offset:2288
	s_waitcnt lgkmcnt(5)
	v_mul_f32_e32 v53, v229, v4
	v_fmac_f32_e32 v53, v228, v3
	v_mul_f32_e32 v52, v231, v6
	v_fmac_f32_e32 v52, v230, v5
	v_add_f32_e32 v52, v53, v52
	s_waitcnt lgkmcnt(4)
	v_mul_f32_e32 v53, v233, v16
	v_mul_f32_e32 v54, v235, v15
	v_fmac_f32_e32 v53, v232, v14
	v_fmac_f32_e32 v54, v234, v13
	v_add_f32_e32 v52, v61, v52
	v_add_f32_e32 v53, v53, v54
	v_add_f32_e32 v53, v52, v53
	v_mul_f32_e64 v52, |v53|, s64
	v_exp_f32_e32 v58, v52
	ds_read_b128 v[220:223], v63 offset:2304
	v_fmamk_f32 v52, v60, 0x3d800000, v51
	v_min_f32_e32 v53, 0, v53
	v_add_f32_e32 v58, 1.0, v58
	v_log_f32_e32 v64, v58
	ds_read_b128 v[224:227], v63 offset:2320
	s_waitcnt lgkmcnt(5)
	v_mul_f32_e32 v55, v237, v2
	v_fmac_f32_e32 v55, v236, v17
	v_mul_f32_e32 v54, v239, v12
	v_fmac_f32_e32 v54, v238, v10
	v_add_f32_e32 v54, v55, v54
	s_waitcnt lgkmcnt(4)
	v_mul_f32_e32 v59, v241, v11
	v_add_f32_e32 v72, v18, v54
	v_fmac_f32_e32 v59, v240, v8
	v_mul_f32_e32 v58, v243, v9
	ds_read_b128 v[228:231], v63 offset:2336
	v_fmac_f32_e32 v58, v242, v7
	v_add_f32_e32 v58, v59, v58
	v_add_f32_e32 v72, v72, v58
	ds_read_b128 v[232:235], v63 offset:2352
	s_waitcnt lgkmcnt(5)
	v_mul_f32_e32 v55, v245, v4
	v_fmac_f32_e32 v55, v244, v3
	v_mul_f32_e32 v54, v247, v6
	v_fmac_f32_e32 v54, v246, v5
	v_add_f32_e32 v54, v55, v54
	s_waitcnt lgkmcnt(4)
	v_mul_f32_e32 v55, v249, v16
	v_mul_f32_e32 v56, v251, v15
	v_fmac_f32_e32 v55, v248, v14
	v_fmac_f32_e32 v56, v250, v13
	v_add_f32_e32 v54, v72, v54
	v_add_f32_e32 v55, v55, v56
	v_add_f32_e32 v72, v54, v55
	v_mul_f32_e64 v54, |v72|, s64
	v_exp_f32_e32 v58, v54
	ds_read_b128 v[236:239], v63 offset:2368
	v_fmac_f32_e32 v53, 0xbf317218, v64
	v_min_f32_e32 v72, 0, v72
	v_add_f32_e32 v58, 1.0, v58
	v_log_f32_e32 v64, v58
	ds_read_b128 v[240:243], v63 offset:2384
	s_waitcnt lgkmcnt(5)
	v_mul_f32_e32 v55, v221, v2
	v_fmac_f32_e32 v55, v220, v17
	v_mul_f32_e32 v54, v223, v12
	v_fmac_f32_e32 v54, v222, v10
	v_add_f32_e32 v54, v55, v54
	s_waitcnt lgkmcnt(4)
	v_mul_f32_e32 v59, v225, v11
	v_add_f32_e32 v73, v18, v54
	v_fmac_f32_e32 v59, v224, v8
	v_mul_f32_e32 v58, v227, v9
	ds_read_b128 v[244:247], v63 offset:2400
	v_fmac_f32_e32 v58, v226, v7
	v_add_f32_e32 v58, v59, v58
	v_add_f32_e32 v73, v73, v58
	ds_read_b128 v[248:251], v63 offset:2416
	s_waitcnt lgkmcnt(5)
	v_mul_f32_e32 v55, v229, v4
	v_fmac_f32_e32 v55, v228, v3
	v_mul_f32_e32 v54, v231, v6
	v_fmac_f32_e32 v54, v230, v5
	v_add_f32_e32 v54, v55, v54
	s_waitcnt lgkmcnt(4)
	v_mul_f32_e32 v55, v233, v16
	v_mul_f32_e32 v56, v235, v15
	v_fmac_f32_e32 v55, v232, v14
	v_fmac_f32_e32 v56, v234, v13
	v_add_f32_e32 v54, v73, v54
	v_add_f32_e32 v55, v55, v56
	v_add_f32_e32 v73, v54, v55
	v_mul_f32_e64 v54, |v73|, s64
	v_exp_f32_e32 v58, v54
	ds_read_b128 v[220:223], v63 offset:2432
	v_fmac_f32_e32 v72, 0xbf317218, v64
	v_fmamk_f32 v53, v53, 0x3d800000, v52
	v_add_f32_e32 v58, 1.0, v58
	v_log_f32_e32 v64, v58
	ds_read_b128 v[224:227], v63 offset:2448
	s_waitcnt lgkmcnt(5)
	v_mul_f32_e32 v55, v237, v2
	v_fmac_f32_e32 v55, v236, v17
	v_mul_f32_e32 v54, v239, v12
	v_fmac_f32_e32 v54, v238, v10
	v_add_f32_e32 v54, v55, v54
	s_waitcnt lgkmcnt(4)
	v_mul_f32_e32 v59, v241, v11
	v_add_f32_e32 v74, v18, v54
	v_fmac_f32_e32 v59, v240, v8
	v_mul_f32_e32 v58, v243, v9
	ds_read_b128 v[228:231], v63 offset:2464
	v_fmac_f32_e32 v58, v242, v7
	v_add_f32_e32 v58, v59, v58
	v_add_f32_e32 v74, v74, v58
	ds_read_b128 v[232:235], v63 offset:2480
	s_waitcnt lgkmcnt(5)
	v_mul_f32_e32 v55, v245, v4
	v_fmac_f32_e32 v55, v244, v3
	v_mul_f32_e32 v54, v247, v6
	v_fmac_f32_e32 v54, v246, v5
	v_add_f32_e32 v54, v55, v54
	s_waitcnt lgkmcnt(4)
	v_mul_f32_e32 v55, v249, v16
	v_mul_f32_e32 v56, v251, v15
	v_fmac_f32_e32 v55, v248, v14
	v_fmac_f32_e32 v56, v250, v13
	v_add_f32_e32 v54, v74, v54
	v_add_f32_e32 v55, v55, v56
	v_add_f32_e32 v60, v54, v55
	v_mul_f32_e64 v54, |v60|, s64
	v_exp_f32_e32 v55, v54
	ds_read_b128 v[236:239], v63 offset:2496
	v_fmamk_f32 v54, v72, 0x3d800000, v53
	v_min_f32_e32 v61, 0, v73
	v_add_f32_e32 v55, 1.0, v55
	ds_read_b128 v[240:243], v63 offset:2512
	v_fmac_f32_e32 v61, 0xbf317218, v64
	v_log_f32_e32 v64, v55
	s_waitcnt lgkmcnt(5)
	v_mul_f32_e32 v57, v221, v2
	v_fmac_f32_e32 v57, v220, v17
	v_mul_f32_e32 v56, v223, v12
	v_fmac_f32_e32 v56, v222, v10
	v_min_f32_e32 v60, 0, v60
	v_add_f32_e32 v56, v57, v56
	v_fmamk_f32 v55, v61, 0x3d800000, v54
	v_fmac_f32_e32 v60, 0xbf317218, v64
	v_add_f32_e32 v61, v18, v56
	s_waitcnt lgkmcnt(4)
	v_mul_f32_e32 v64, v225, v11
	ds_read_b128 v[244:247], v63 offset:2528
	v_fmac_f32_e32 v64, v224, v8
	v_mul_f32_e32 v72, v227, v9
	v_fmac_f32_e32 v72, v226, v7
	v_add_f32_e32 v64, v64, v72
	ds_read_b128 v[248:251], v63 offset:2544
	s_waitcnt lgkmcnt(5)
	v_mul_f32_e32 v57, v229, v4
	v_fmac_f32_e32 v57, v228, v3
	v_mul_f32_e32 v56, v231, v6
	v_fmac_f32_e32 v56, v230, v5
	v_add_f32_e32 v56, v57, v56
	s_waitcnt lgkmcnt(4)
	v_mul_f32_e32 v57, v233, v16
	v_mul_f32_e32 v58, v235, v15
	v_add_f32_e32 v61, v61, v64
	v_fmac_f32_e32 v57, v232, v14
	v_fmac_f32_e32 v58, v234, v13
	v_add_f32_e32 v56, v61, v56
	v_add_f32_e32 v57, v57, v58
	v_add_f32_e32 v57, v56, v57
	v_mul_f32_e64 v56, |v57|, s64
	v_exp_f32_e32 v64, v56
	v_fmamk_f32 v56, v60, 0x3d800000, v55
	ds_read_b128 v[220:223], v63 offset:2560
	ds_read_b128 v[224:227], v63 offset:2576
	v_add_f32_e32 v64, 1.0, v64
	v_log_f32_e32 v64, v64
	v_min_f32_e32 v57, 0, v57
	s_waitcnt lgkmcnt(5)
	v_mul_f32_e32 v59, v237, v2
	v_fmac_f32_e32 v59, v236, v17
	v_mul_f32_e32 v58, v239, v12
	v_fmac_f32_e32 v58, v238, v10
	v_add_f32_e32 v58, v59, v58
	s_waitcnt lgkmcnt(4)
	v_mul_f32_e32 v73, v241, v11
	v_add_f32_e32 v76, v18, v58
	v_fmac_f32_e32 v73, v240, v8
	v_mul_f32_e32 v72, v243, v9
	ds_read_b128 v[228:231], v63 offset:2592
	v_fmac_f32_e32 v72, v242, v7
	v_add_f32_e32 v72, v73, v72
	v_add_f32_e32 v76, v76, v72
	ds_read_b128 v[232:235], v63 offset:2608
	s_waitcnt lgkmcnt(5)
	v_mul_f32_e32 v59, v245, v4
	v_fmac_f32_e32 v59, v244, v3
	v_mul_f32_e32 v58, v247, v6
	v_fmac_f32_e32 v58, v246, v5
	v_add_f32_e32 v58, v59, v58
	s_waitcnt lgkmcnt(4)
	v_mul_f32_e32 v59, v249, v16
	v_mul_f32_e32 v60, v251, v15
	v_fmac_f32_e32 v59, v248, v14
	v_fmac_f32_e32 v60, v250, v13
	v_add_f32_e32 v58, v76, v58
	v_add_f32_e32 v59, v59, v60
	v_add_f32_e32 v76, v58, v59
	v_mul_f32_e64 v58, |v76|, s64
	v_exp_f32_e32 v72, v58
	ds_read_b128 v[236:239], v63 offset:2624
	v_fmac_f32_e32 v57, 0xbf317218, v64
	v_min_f32_e32 v76, 0, v76
	v_add_f32_e32 v64, 1.0, v72
	ds_read_b128 v[240:243], v63 offset:2640
	s_waitcnt lgkmcnt(5)
	v_mul_f32_e32 v59, v221, v2
	v_fmac_f32_e32 v59, v220, v17
	v_mul_f32_e32 v58, v223, v12
	v_fmac_f32_e32 v58, v222, v10
	v_add_f32_e32 v58, v59, v58
	s_waitcnt lgkmcnt(4)
	v_mul_f32_e32 v73, v225, v11
	v_add_f32_e32 v77, v18, v58
	v_fmac_f32_e32 v73, v224, v8
	v_mul_f32_e32 v72, v227, v9
	ds_read_b128 v[244:247], v63 offset:2656
	v_fmac_f32_e32 v72, v226, v7
	v_add_f32_e32 v72, v73, v72
	v_add_f32_e32 v77, v77, v72
	ds_read_b128 v[248:251], v63 offset:2672
	s_waitcnt lgkmcnt(5)
	v_mul_f32_e32 v59, v229, v4
	v_fmac_f32_e32 v59, v228, v3
	v_mul_f32_e32 v58, v231, v6
	v_fmac_f32_e32 v58, v230, v5
	v_add_f32_e32 v58, v59, v58
	s_waitcnt lgkmcnt(4)
	v_mul_f32_e32 v59, v233, v16
	v_mul_f32_e32 v60, v235, v15
	v_fmac_f32_e32 v59, v232, v14
	v_fmac_f32_e32 v60, v234, v13
	v_add_f32_e32 v58, v77, v58
	v_add_f32_e32 v59, v59, v60
	v_add_f32_e32 v77, v58, v59
	v_mul_f32_e64 v58, |v77|, s64
	v_log_f32_e32 v64, v64
	v_exp_f32_e32 v72, v58
	ds_read_b128 v[220:223], v63 offset:2688
	v_fmamk_f32 v57, v57, 0x3d800000, v56
	v_fmac_f32_e32 v76, 0xbf317218, v64
	v_add_f32_e32 v64, 1.0, v72
	ds_read_b128 v[224:227], v63 offset:2704
	s_waitcnt lgkmcnt(5)
	v_mul_f32_e32 v59, v237, v2
	v_fmac_f32_e32 v59, v236, v17
	v_mul_f32_e32 v58, v239, v12
	v_fmac_f32_e32 v58, v238, v10
	v_add_f32_e32 v58, v59, v58
	s_waitcnt lgkmcnt(4)
	v_mul_f32_e32 v73, v241, v11
	v_add_f32_e32 v78, v18, v58
	v_fmac_f32_e32 v73, v240, v8
	v_mul_f32_e32 v72, v243, v9
	ds_read_b128 v[228:231], v63 offset:2720
	v_fmac_f32_e32 v72, v242, v7
	v_add_f32_e32 v72, v73, v72
	v_add_f32_e32 v78, v78, v72
	ds_read_b128 v[232:235], v63 offset:2736
	s_waitcnt lgkmcnt(5)
	v_mul_f32_e32 v59, v245, v4
	v_fmac_f32_e32 v59, v244, v3
	v_mul_f32_e32 v58, v247, v6
	v_fmac_f32_e32 v58, v246, v5
	v_add_f32_e32 v58, v59, v58
	s_waitcnt lgkmcnt(4)
	v_mul_f32_e32 v59, v249, v16
	v_mul_f32_e32 v60, v251, v15
	v_fmac_f32_e32 v59, v248, v14
	v_fmac_f32_e32 v60, v250, v13
	v_add_f32_e32 v58, v78, v58
	v_add_f32_e32 v59, v59, v60
	v_add_f32_e32 v60, v58, v59
	v_mul_f32_e64 v58, |v60|, s64
	v_exp_f32_e32 v59, v58
	v_log_f32_e32 v64, v64
	v_min_f32_e32 v61, 0, v77
	ds_read_b128 v[236:239], v63 offset:2752
	v_add_f32_e32 v59, 1.0, v59
	v_fmac_f32_e32 v61, 0xbf317218, v64
	v_log_f32_e32 v64, v59
	v_fmamk_f32 v58, v76, 0x3d800000, v57
	ds_read_b128 v[240:243], v63 offset:2768
	v_min_f32_e32 v60, 0, v60
	v_fmamk_f32 v59, v61, 0x3d800000, v58
	v_fmac_f32_e32 v60, 0xbf317218, v64
	s_waitcnt lgkmcnt(5)
	v_mul_f32_e32 v61, v221, v2
	v_mul_f32_e32 v64, v223, v12
	v_fmac_f32_e32 v61, v220, v17
	v_fmac_f32_e32 v64, v222, v10
	ds_read_b128 v[244:247], v63 offset:2784
	v_add_f32_e32 v61, v61, v64
	s_waitcnt lgkmcnt(5)
	v_mul_f32_e32 v64, v225, v11
	v_fmac_f32_e32 v64, v224, v8
	v_mul_f32_e32 v76, v227, v9
	v_fmac_f32_e32 v76, v226, v7
	v_add_f32_e32 v61, v18, v61
	v_add_f32_e32 v64, v64, v76
	ds_read_b128 v[248:251], v63 offset:2800
	v_add_f32_e32 v61, v61, v64
	s_waitcnt lgkmcnt(5)
	v_mul_f32_e32 v64, v229, v4
	v_fmac_f32_e32 v64, v228, v3
	v_mul_f32_e32 v72, v231, v6
	v_fmac_f32_e32 v72, v230, v5
	v_add_f32_e32 v64, v64, v72
	v_add_f32_e32 v61, v61, v64
	s_waitcnt lgkmcnt(4)
	v_mul_f32_e32 v64, v233, v16
	v_mul_f32_e32 v72, v235, v15
	v_fmac_f32_e32 v64, v232, v14
	v_fmac_f32_e32 v72, v234, v13
	v_add_f32_e32 v64, v64, v72
	ds_read_b128 v[220:223], v63 offset:2816
	ds_read_b128 v[224:227], v63 offset:2832
	v_add_f32_e32 v61, v61, v64
	v_mul_f32_e64 v64, |v61|, s64
	v_exp_f32_e32 v64, v64
	s_waitcnt lgkmcnt(5)
	v_mul_f32_e32 v73, v237, v2
	v_fmac_f32_e32 v73, v236, v17
	v_mul_f32_e32 v72, v239, v12
	v_fmac_f32_e32 v72, v238, v10
	v_add_f32_e32 v72, v73, v72
	s_waitcnt lgkmcnt(4)
	v_mul_f32_e32 v77, v241, v11
	v_add_f32_e32 v80, v18, v72
	v_fmac_f32_e32 v77, v240, v8
	v_mul_f32_e32 v76, v243, v9
	ds_read_b128 v[228:231], v63 offset:2848
	v_fmac_f32_e32 v76, v242, v7
	v_add_f32_e32 v76, v77, v76
	v_add_f32_e32 v80, v80, v76
	ds_read_b128 v[232:235], v63 offset:2864
	s_waitcnt lgkmcnt(5)
	v_mul_f32_e32 v73, v245, v4
	v_fmac_f32_e32 v73, v244, v3
	v_mul_f32_e32 v72, v247, v6
	v_fmac_f32_e32 v72, v246, v5
	v_add_f32_e32 v72, v73, v72
	s_waitcnt lgkmcnt(4)
	v_mul_f32_e32 v73, v249, v16
	v_mul_f32_e32 v74, v251, v15
	v_fmac_f32_e32 v73, v248, v14
	v_fmac_f32_e32 v74, v250, v13
	v_add_f32_e32 v72, v80, v72
	v_add_f32_e32 v73, v73, v74
	v_add_f32_e32 v80, v72, v73
	v_add_f32_e32 v64, 1.0, v64
	v_mul_f32_e64 v72, |v80|, s64
	v_log_f32_e32 v64, v64
	v_exp_f32_e32 v76, v72
	ds_read_b128 v[236:239], v63 offset:2880
	v_min_f32_e32 v61, 0, v61
	v_fmac_f32_e32 v61, 0xbf317218, v64
	v_add_f32_e32 v64, 1.0, v76
	ds_read_b128 v[240:243], v63 offset:2896
	s_waitcnt lgkmcnt(5)
	v_mul_f32_e32 v73, v221, v2
	v_fmac_f32_e32 v73, v220, v17
	v_mul_f32_e32 v72, v223, v12
	v_fmac_f32_e32 v72, v222, v10
	v_add_f32_e32 v72, v73, v72
	s_waitcnt lgkmcnt(4)
	v_mul_f32_e32 v77, v225, v11
	v_add_f32_e32 v81, v18, v72
	v_fmac_f32_e32 v77, v224, v8
	v_mul_f32_e32 v76, v227, v9
	ds_read_b128 v[244:247], v63 offset:2912
	v_fmac_f32_e32 v76, v226, v7
	v_add_f32_e32 v76, v77, v76
	v_add_f32_e32 v81, v81, v76
	ds_read_b128 v[248:251], v63 offset:2928
	s_waitcnt lgkmcnt(5)
	v_mul_f32_e32 v73, v229, v4
	v_fmac_f32_e32 v73, v228, v3
	v_mul_f32_e32 v72, v231, v6
	v_fmac_f32_e32 v72, v230, v5
	v_add_f32_e32 v72, v73, v72
	s_waitcnt lgkmcnt(4)
	v_mul_f32_e32 v73, v233, v16
	v_mul_f32_e32 v74, v235, v15
	v_fmac_f32_e32 v73, v232, v14
	v_fmac_f32_e32 v74, v234, v13
	v_add_f32_e32 v72, v81, v72
	v_add_f32_e32 v73, v73, v74
	v_add_f32_e32 v81, v72, v73
	v_mul_f32_e64 v72, |v81|, s64
	v_log_f32_e32 v64, v64
	v_exp_f32_e32 v76, v72
	ds_read_b128 v[220:223], v63 offset:2944
	v_min_f32_e32 v80, 0, v80
	v_fmac_f32_e32 v80, 0xbf317218, v64
	v_add_f32_e32 v64, 1.0, v76
	ds_read_b128 v[224:227], v63 offset:2960
	v_log_f32_e32 v82, v64
	s_waitcnt lgkmcnt(5)
	v_mul_f32_e32 v64, v237, v2
	v_fmac_f32_e32 v64, v236, v17
	v_mul_f32_e32 v72, v239, v12
	v_fmac_f32_e32 v72, v238, v10
	v_add_f32_e32 v64, v64, v72
	s_waitcnt lgkmcnt(4)
	v_mul_f32_e32 v77, v241, v11
	ds_read_b128 v[228:231], v63 offset:2976
	v_fmac_f32_e32 v77, v240, v8
	v_mul_f32_e32 v76, v243, v9
	v_fmac_f32_e32 v76, v242, v7
	v_add_f32_e32 v64, v18, v64
	v_add_f32_e32 v76, v77, v76
	v_add_f32_e32 v64, v64, v76
	ds_read_b128 v[232:235], v63 offset:2992
	s_waitcnt lgkmcnt(5)
	v_mul_f32_e32 v73, v245, v4
	v_fmac_f32_e32 v73, v244, v3
	v_mul_f32_e32 v72, v247, v6
	v_fmac_f32_e32 v72, v246, v5
	v_add_f32_e32 v72, v73, v72
	v_add_f32_e32 v64, v64, v72
	s_waitcnt lgkmcnt(4)
	v_mul_f32_e32 v72, v249, v16
	v_mul_f32_e32 v73, v251, v15
	v_fmac_f32_e32 v72, v248, v14
	v_fmac_f32_e32 v73, v250, v13
	v_add_f32_e32 v72, v72, v73
	v_add_f32_e32 v73, v64, v72
	v_mul_f32_e64 v64, |v73|, s64
	v_exp_f32_e32 v72, v64
	v_fmamk_f32 v60, v60, 0x3d800000, v59
	ds_read_b128 v[236:239], v63 offset:3008
	v_fmamk_f32 v61, v61, 0x3d800000, v60
	v_add_f32_e32 v72, 1.0, v72
	v_log_f32_e32 v79, v72
	v_min_f32_e32 v78, 0, v81
	v_fmamk_f32 v64, v80, 0x3d800000, v61
	v_fmac_f32_e32 v78, 0xbf317218, v82
	v_min_f32_e32 v73, 0, v73
	v_fmamk_f32 v72, v78, 0x3d800000, v64
	v_fmac_f32_e32 v73, 0xbf317218, v79
	ds_read_b128 v[240:243], v63 offset:3024
	s_waitcnt lgkmcnt(5)
	v_mul_f32_e32 v75, v221, v2
	v_fmac_f32_e32 v75, v220, v17
	v_mul_f32_e32 v74, v223, v12
	v_fmac_f32_e32 v74, v222, v10
	v_add_f32_e32 v74, v75, v74
	s_waitcnt lgkmcnt(4)
	v_mul_f32_e32 v79, v225, v11
	v_add_f32_e32 v82, v18, v74
	v_fmac_f32_e32 v79, v224, v8
	v_mul_f32_e32 v78, v227, v9
	ds_read_b128 v[244:247], v63 offset:3040
	v_fmac_f32_e32 v78, v226, v7
	v_add_f32_e32 v78, v79, v78
	v_add_f32_e32 v82, v82, v78
	ds_read_b128 v[248:251], v63 offset:3056
	s_waitcnt lgkmcnt(5)
	v_mul_f32_e32 v75, v229, v4
	v_fmac_f32_e32 v75, v228, v3
	v_mul_f32_e32 v74, v231, v6
	v_fmac_f32_e32 v74, v230, v5
	v_add_f32_e32 v74, v75, v74
	s_waitcnt lgkmcnt(4)
	v_mul_f32_e32 v75, v233, v16
	v_mul_f32_e32 v76, v235, v15
	v_fmac_f32_e32 v75, v232, v14
	v_fmac_f32_e32 v76, v234, v13
	v_add_f32_e32 v74, v82, v74
	v_add_f32_e32 v75, v75, v76
	v_add_f32_e32 v78, v74, v75
	v_mul_f32_e64 v74, |v78|, s64
	v_exp_f32_e32 v79, v74
	ds_read_b128 v[220:223], v63 offset:3072
	v_min_f32_e32 v82, 0, v78
	v_fmamk_f32 v73, v73, 0x3d800000, v72
	v_add_f32_e32 v78, 1.0, v79
	v_log_f32_e32 v83, v78
	ds_read_b128 v[224:227], v63 offset:3088
	s_waitcnt lgkmcnt(5)
	v_mul_f32_e32 v75, v237, v2
	v_fmac_f32_e32 v75, v236, v17
	v_mul_f32_e32 v74, v239, v12
	v_fmac_f32_e32 v74, v238, v10
	v_add_f32_e32 v74, v75, v74
	s_waitcnt lgkmcnt(4)
	v_mul_f32_e32 v79, v241, v11
	v_add_f32_e32 v115, v18, v74
	v_fmac_f32_e32 v79, v240, v8
	v_mul_f32_e32 v78, v243, v9
	ds_read_b128 v[228:231], v63 offset:3104
	v_fmac_f32_e32 v78, v242, v7
	v_add_f32_e32 v78, v79, v78
	v_add_f32_e32 v115, v115, v78
	ds_read_b128 v[232:235], v63 offset:3120
	s_waitcnt lgkmcnt(5)
	v_mul_f32_e32 v75, v245, v4
	v_fmac_f32_e32 v75, v244, v3
	v_mul_f32_e32 v74, v247, v6
	v_fmac_f32_e32 v74, v246, v5
	v_add_f32_e32 v74, v75, v74
	s_waitcnt lgkmcnt(4)
	v_mul_f32_e32 v75, v249, v16
	v_mul_f32_e32 v76, v251, v15
	v_fmac_f32_e32 v75, v248, v14
	v_fmac_f32_e32 v76, v250, v13
	v_add_f32_e32 v74, v115, v74
	v_add_f32_e32 v75, v75, v76
	v_add_f32_e32 v75, v74, v75
	v_mul_f32_e64 v74, |v75|, s64
	v_exp_f32_e32 v80, v74
	ds_read_b128 v[236:239], v63 offset:3136
	v_fmac_f32_e32 v82, 0xbf317218, v83
	v_fmamk_f32 v74, v82, 0x3d800000, v73
	v_add_f32_e32 v80, 1.0, v80
	v_log_f32_e32 v115, v80
	ds_read_b128 v[240:243], v63 offset:3152
	s_waitcnt lgkmcnt(5)
	v_mul_f32_e32 v77, v221, v2
	v_fmac_f32_e32 v77, v220, v17
	v_mul_f32_e32 v76, v223, v12
	v_fmac_f32_e32 v76, v222, v10
	v_add_f32_e32 v76, v77, v76
	s_waitcnt lgkmcnt(4)
	v_mul_f32_e32 v81, v225, v11
	v_add_f32_e32 v116, v18, v76
	v_fmac_f32_e32 v81, v224, v8
	v_mul_f32_e32 v80, v227, v9
	ds_read_b128 v[244:247], v63 offset:3168
	v_fmac_f32_e32 v80, v226, v7
	v_add_f32_e32 v80, v81, v80
	v_add_f32_e32 v116, v116, v80
	ds_read_b128 v[248:251], v63 offset:3184
	s_waitcnt lgkmcnt(5)
	v_mul_f32_e32 v77, v229, v4
	v_fmac_f32_e32 v77, v228, v3
	v_mul_f32_e32 v76, v231, v6
	v_fmac_f32_e32 v76, v230, v5
	v_add_f32_e32 v76, v77, v76
	s_waitcnt lgkmcnt(4)
	v_mul_f32_e32 v77, v233, v16
	v_mul_f32_e32 v78, v235, v15
	v_fmac_f32_e32 v77, v232, v14
	v_fmac_f32_e32 v78, v234, v13
	v_add_f32_e32 v76, v116, v76
	v_add_f32_e32 v77, v77, v78
	v_add_f32_e32 v116, v76, v77
	v_mul_f32_e64 v76, |v116|, s64
	v_exp_f32_e32 v80, v76
	ds_read_b128 v[220:223], v63 offset:3200
	v_min_f32_e32 v75, 0, v75
	v_fmac_f32_e32 v75, 0xbf317218, v115
	v_add_f32_e32 v80, 1.0, v80
	v_log_f32_e32 v115, v80
	ds_read_b128 v[224:227], v63 offset:3216
	s_waitcnt lgkmcnt(5)
	v_mul_f32_e32 v77, v237, v2
	v_fmac_f32_e32 v77, v236, v17
	v_mul_f32_e32 v76, v239, v12
	v_fmac_f32_e32 v76, v238, v10
	v_add_f32_e32 v76, v77, v76
	s_waitcnt lgkmcnt(4)
	v_mul_f32_e32 v81, v241, v11
	v_add_f32_e32 v117, v18, v76
	v_fmac_f32_e32 v81, v240, v8
	v_mul_f32_e32 v80, v243, v9
	ds_read_b128 v[228:231], v63 offset:3232
	v_fmac_f32_e32 v80, v242, v7
	v_add_f32_e32 v80, v81, v80
	v_add_f32_e32 v117, v117, v80
	ds_read_b128 v[232:235], v63 offset:3248
	s_waitcnt lgkmcnt(5)
	v_mul_f32_e32 v77, v245, v4
	v_fmac_f32_e32 v77, v244, v3
	v_mul_f32_e32 v76, v247, v6
	v_fmac_f32_e32 v76, v246, v5
	v_add_f32_e32 v76, v77, v76
	s_waitcnt lgkmcnt(4)
	v_mul_f32_e32 v77, v249, v16
	v_mul_f32_e32 v78, v251, v15
	v_fmac_f32_e32 v77, v248, v14
	v_fmac_f32_e32 v78, v250, v13
	v_add_f32_e32 v76, v117, v76
	v_add_f32_e32 v77, v77, v78
	v_add_f32_e32 v77, v76, v77
	ds_read_b128 v[236:239], v63 offset:3264
	v_mul_f32_e64 v76, |v77|, s64
	v_exp_f32_e32 v76, v76
	v_min_f32_e32 v82, 0, v116
	ds_read_b128 v[240:243], v63 offset:3280
	s_waitcnt lgkmcnt(5)
	v_mul_f32_e32 v79, v221, v2
	v_add_f32_e32 v76, 1.0, v76
	v_fmac_f32_e32 v79, v220, v17
	v_mul_f32_e32 v78, v223, v12
	v_log_f32_e32 v83, v76
	v_fmac_f32_e32 v78, v222, v10
	v_fmamk_f32 v75, v75, 0x3d800000, v74
	v_fmac_f32_e32 v82, 0xbf317218, v115
	v_add_f32_e32 v78, v79, v78
	v_fmamk_f32 v76, v82, 0x3d800000, v75
	v_add_f32_e32 v82, v18, v78
	ds_read_b128 v[244:247], v63 offset:3296
	v_min_f32_e32 v77, 0, v77
	v_fmac_f32_e32 v77, 0xbf317218, v83
	s_waitcnt lgkmcnt(5)
	v_mul_f32_e32 v83, v225, v11
	v_mul_f32_e32 v115, v227, v9
	v_fmac_f32_e32 v83, v224, v8
	v_fmac_f32_e32 v115, v226, v7
	ds_read_b128 v[248:251], v63 offset:3312
	s_waitcnt lgkmcnt(5)
	v_mul_f32_e32 v79, v229, v4
	v_fmac_f32_e32 v79, v228, v3
	v_mul_f32_e32 v78, v231, v6
	v_fmac_f32_e32 v78, v230, v5
	v_add_f32_e32 v83, v83, v115
	v_add_f32_e32 v78, v79, v78
	s_waitcnt lgkmcnt(4)
	v_mul_f32_e32 v79, v233, v16
	v_mul_f32_e32 v80, v235, v15
	v_add_f32_e32 v82, v82, v83
	v_fmac_f32_e32 v79, v232, v14
	v_fmac_f32_e32 v80, v234, v13
	v_add_f32_e32 v78, v82, v78
	v_add_f32_e32 v79, v79, v80
	v_add_f32_e32 v82, v78, v79
	v_mul_f32_e64 v78, |v82|, s64
	v_exp_f32_e32 v83, v78
	ds_read_b128 v[220:223], v63 offset:3328
	ds_read_b128 v[224:227], v63 offset:3344
	v_min_f32_e32 v115, 0, v82
	v_add_f32_e32 v82, 1.0, v83
	v_log_f32_e32 v82, v82
	s_waitcnt lgkmcnt(5)
	v_mul_f32_e32 v79, v237, v2
	v_fmac_f32_e32 v79, v236, v17
	v_mul_f32_e32 v78, v239, v12
	v_fmac_f32_e32 v78, v238, v10
	v_add_f32_e32 v78, v79, v78
	s_waitcnt lgkmcnt(4)
	v_mul_f32_e32 v117, v241, v11
	v_add_f32_e32 v83, v18, v78
	v_fmac_f32_e32 v117, v240, v8
	v_mul_f32_e32 v116, v243, v9
	ds_read_b128 v[228:231], v63 offset:3360
	v_fmac_f32_e32 v116, v242, v7
	v_add_f32_e32 v116, v117, v116
	v_add_f32_e32 v83, v83, v116
	ds_read_b128 v[232:235], v63 offset:3376
	s_waitcnt lgkmcnt(5)
	v_mul_f32_e32 v79, v245, v4
	v_fmac_f32_e32 v79, v244, v3
	v_mul_f32_e32 v78, v247, v6
	v_fmac_f32_e32 v78, v246, v5
	v_add_f32_e32 v78, v79, v78
	s_waitcnt lgkmcnt(4)
	v_mul_f32_e32 v79, v249, v16
	v_mul_f32_e32 v80, v251, v15
	v_fmac_f32_e32 v79, v248, v14
	v_fmac_f32_e32 v80, v250, v13
	v_add_f32_e32 v78, v83, v78
	v_add_f32_e32 v79, v79, v80
	v_add_f32_e32 v79, v78, v79
	v_mul_f32_e64 v78, |v79|, s64
	v_exp_f32_e32 v116, v78
	v_fmac_f32_e32 v115, 0xbf317218, v82
	ds_read_b128 v[236:239], v63 offset:3392
	v_fmamk_f32 v77, v77, 0x3d800000, v76
	v_fmamk_f32 v78, v115, 0x3d800000, v77
	v_add_f32_e32 v115, 1.0, v116
	ds_read_b128 v[240:243], v63 offset:3408
	s_waitcnt lgkmcnt(5)
	v_mul_f32_e32 v81, v221, v2
	v_fmac_f32_e32 v81, v220, v17
	v_mul_f32_e32 v80, v223, v12
	v_fmac_f32_e32 v80, v222, v10
	v_add_f32_e32 v80, v81, v80
	s_waitcnt lgkmcnt(4)
	v_mul_f32_e32 v117, v225, v11
	v_add_f32_e32 v120, v18, v80
	v_fmac_f32_e32 v117, v224, v8
	v_mul_f32_e32 v116, v227, v9
	ds_read_b128 v[244:247], v63 offset:3424
	v_fmac_f32_e32 v116, v226, v7
	v_add_f32_e32 v116, v117, v116
	v_add_f32_e32 v120, v120, v116
	ds_read_b128 v[248:251], v63 offset:3440
	s_waitcnt lgkmcnt(5)
	v_mul_f32_e32 v81, v229, v4
	v_fmac_f32_e32 v81, v228, v3
	v_mul_f32_e32 v80, v231, v6
	v_fmac_f32_e32 v80, v230, v5
	v_add_f32_e32 v80, v81, v80
	s_waitcnt lgkmcnt(4)
	v_mul_f32_e32 v81, v233, v16
	v_mul_f32_e32 v82, v235, v15
	v_fmac_f32_e32 v81, v232, v14
	v_fmac_f32_e32 v82, v234, v13
	v_add_f32_e32 v80, v120, v80
	v_add_f32_e32 v81, v81, v82
	v_add_f32_e32 v120, v80, v81
	v_mul_f32_e64 v80, |v120|, s64
	v_log_f32_e32 v115, v115
	v_exp_f32_e32 v116, v80
	ds_read_b128 v[220:223], v63 offset:3456
	v_min_f32_e32 v79, 0, v79
	v_fmac_f32_e32 v79, 0xbf317218, v115
	v_add_f32_e32 v115, 1.0, v116
	ds_read_b128 v[224:227], v63 offset:3472
	s_waitcnt lgkmcnt(5)
	v_mul_f32_e32 v81, v237, v2
	v_fmac_f32_e32 v81, v236, v17
	v_mul_f32_e32 v80, v239, v12
	v_fmac_f32_e32 v80, v238, v10
	v_add_f32_e32 v80, v81, v80
	s_waitcnt lgkmcnt(4)
	v_mul_f32_e32 v117, v241, v11
	v_add_f32_e32 v121, v18, v80
	v_fmac_f32_e32 v117, v240, v8
	v_mul_f32_e32 v116, v243, v9
	ds_read_b128 v[228:231], v63 offset:3488
	v_fmac_f32_e32 v116, v242, v7
	v_add_f32_e32 v116, v117, v116
	v_add_f32_e32 v121, v121, v116
	ds_read_b128 v[232:235], v63 offset:3504
	s_waitcnt lgkmcnt(5)
	v_mul_f32_e32 v81, v245, v4
	v_fmac_f32_e32 v81, v244, v3
	v_mul_f32_e32 v80, v247, v6
	v_fmac_f32_e32 v80, v246, v5
	v_add_f32_e32 v80, v81, v80
	s_waitcnt lgkmcnt(4)
	v_mul_f32_e32 v81, v249, v16
	v_mul_f32_e32 v82, v251, v15
	v_fmac_f32_e32 v81, v248, v14
	v_fmac_f32_e32 v82, v250, v13
	v_add_f32_e32 v80, v121, v80
	v_add_f32_e32 v81, v81, v82
	v_add_f32_e32 v81, v80, v81
	v_mul_f32_e64 v80, |v81|, s64
	v_exp_f32_e32 v80, v80
	v_log_f32_e32 v115, v115
	ds_read_b128 v[236:239], v63 offset:3520
	v_min_f32_e32 v82, 0, v120
	v_add_f32_e32 v80, 1.0, v80
	v_log_f32_e32 v83, v80
	ds_read_b128 v[240:243], v63 offset:3536
	v_fmamk_f32 v79, v79, 0x3d800000, v78
	v_fmac_f32_e32 v82, 0xbf317218, v115
	v_min_f32_e32 v81, 0, v81
	v_fmamk_f32 v80, v82, 0x3d800000, v79
	v_fmac_f32_e32 v81, 0xbf317218, v83
	s_waitcnt lgkmcnt(5)
	v_mul_f32_e32 v82, v221, v2
	v_mul_f32_e32 v83, v223, v12
	v_fmac_f32_e32 v82, v220, v17
	v_fmac_f32_e32 v83, v222, v10
	ds_read_b128 v[244:247], v63 offset:3552
	v_add_f32_e32 v82, v82, v83
	s_waitcnt lgkmcnt(5)
	v_mul_f32_e32 v83, v225, v11
	v_mul_f32_e32 v115, v227, v9
	v_fmac_f32_e32 v83, v224, v8
	v_fmac_f32_e32 v115, v226, v7
	ds_read_b128 v[248:251], v63 offset:3568
	v_add_f32_e32 v82, v18, v82
	v_add_f32_e32 v83, v83, v115
	v_add_f32_e32 v82, v82, v83
	s_waitcnt lgkmcnt(5)
	v_mul_f32_e32 v83, v229, v4
	v_mul_f32_e32 v115, v231, v6
	v_fmac_f32_e32 v83, v228, v3
	v_fmac_f32_e32 v115, v230, v5
	ds_read_b128 v[220:223], v63 offset:3584
	v_add_f32_e32 v83, v83, v115
	v_add_f32_e32 v82, v82, v83
	s_waitcnt lgkmcnt(5)
	v_mul_f32_e32 v83, v233, v16
	v_mul_f32_e32 v115, v235, v15
	v_fmac_f32_e32 v83, v232, v14
	v_fmac_f32_e32 v115, v234, v13
	ds_read_b128 v[224:227], v63 offset:3600
	v_add_f32_e32 v83, v83, v115
	s_waitcnt lgkmcnt(5)
	v_mul_f32_e32 v115, v237, v2
	v_fmac_f32_e32 v115, v236, v17
	v_mul_f32_e32 v116, v239, v12
	v_fmac_f32_e32 v116, v238, v10
	v_add_f32_e32 v115, v115, v116
	s_waitcnt lgkmcnt(4)
	v_mul_f32_e32 v121, v241, v11
	ds_read_b128 v[228:231], v63 offset:3616
	v_fmac_f32_e32 v121, v240, v8
	v_mul_f32_e32 v120, v243, v9
	v_fmac_f32_e32 v120, v242, v7
	v_add_f32_e32 v115, v18, v115
	v_add_f32_e32 v120, v121, v120
	v_add_f32_e32 v115, v115, v120
	ds_read_b128 v[232:235], v63 offset:3632
	s_waitcnt lgkmcnt(5)
	v_mul_f32_e32 v117, v245, v4
	v_fmac_f32_e32 v117, v244, v3
	v_mul_f32_e32 v116, v247, v6
	v_add_f32_e32 v82, v82, v83
	v_fmac_f32_e32 v116, v246, v5
	v_mul_f32_e64 v83, |v82|, s64
	v_add_f32_e32 v116, v117, v116
	v_exp_f32_e32 v83, v83
	v_add_f32_e32 v115, v115, v116
	s_waitcnt lgkmcnt(4)
	v_mul_f32_e32 v116, v249, v16
	v_mul_f32_e32 v117, v251, v15
	v_fmac_f32_e32 v116, v248, v14
	v_fmac_f32_e32 v117, v250, v13
	v_add_f32_e32 v116, v116, v117
	v_add_f32_e32 v115, v115, v116
	v_add_f32_e32 v83, 1.0, v83
	v_mul_f32_e64 v116, |v115|, s64
	v_log_f32_e32 v83, v83
	v_exp_f32_e32 v120, v116
	ds_read_b128 v[236:239], v63 offset:3648
	v_min_f32_e32 v82, 0, v82
	v_fmac_f32_e32 v82, 0xbf317218, v83
	v_add_f32_e32 v83, 1.0, v120
	ds_read_b128 v[240:243], v63 offset:3664
	s_waitcnt lgkmcnt(5)
	v_mul_f32_e32 v117, v221, v2
	v_fmac_f32_e32 v117, v220, v17
	v_mul_f32_e32 v116, v223, v12
	v_fmac_f32_e32 v116, v222, v10
	v_add_f32_e32 v116, v117, v116
	s_waitcnt lgkmcnt(4)
	v_mul_f32_e32 v121, v225, v11
	v_add_f32_e32 v124, v18, v116
	v_fmac_f32_e32 v121, v224, v8
	v_mul_f32_e32 v120, v227, v9
	ds_read_b128 v[244:247], v63 offset:3680
	v_fmac_f32_e32 v120, v226, v7
	v_add_f32_e32 v120, v121, v120
	v_add_f32_e32 v124, v124, v120
	ds_read_b128 v[248:251], v63 offset:3696
	s_waitcnt lgkmcnt(5)
	v_mul_f32_e32 v117, v229, v4
	v_fmac_f32_e32 v117, v228, v3
	v_mul_f32_e32 v116, v231, v6
	v_fmac_f32_e32 v116, v230, v5
	v_add_f32_e32 v116, v117, v116
	s_waitcnt lgkmcnt(4)
	v_mul_f32_e32 v117, v233, v16
	v_mul_f32_e32 v118, v235, v15
	v_fmac_f32_e32 v117, v232, v14
	v_fmac_f32_e32 v118, v234, v13
	v_add_f32_e32 v116, v124, v116
	v_add_f32_e32 v117, v117, v118
	v_add_f32_e32 v124, v116, v117
	v_mul_f32_e64 v116, |v124|, s64
	v_log_f32_e32 v83, v83
	v_exp_f32_e32 v120, v116
	ds_read_b128 v[220:223], v63 offset:3712
	v_min_f32_e32 v115, 0, v115
	v_fmac_f32_e32 v115, 0xbf317218, v83
	v_add_f32_e32 v83, 1.0, v120
	ds_read_b128 v[224:227], v63 offset:3728
	v_log_f32_e32 v125, v83
	s_waitcnt lgkmcnt(5)
	v_mul_f32_e32 v83, v237, v2
	v_fmac_f32_e32 v83, v236, v17
	v_mul_f32_e32 v116, v239, v12
	v_fmac_f32_e32 v116, v238, v10
	v_add_f32_e32 v83, v83, v116
	s_waitcnt lgkmcnt(4)
	v_mul_f32_e32 v121, v241, v11
	ds_read_b128 v[228:231], v63 offset:3744
	v_fmac_f32_e32 v121, v240, v8
	v_mul_f32_e32 v120, v243, v9
	v_fmac_f32_e32 v120, v242, v7
	v_add_f32_e32 v83, v18, v83
	v_add_f32_e32 v120, v121, v120
	v_add_f32_e32 v83, v83, v120
	ds_read_b128 v[232:235], v63 offset:3760
	s_waitcnt lgkmcnt(5)
	v_mul_f32_e32 v117, v245, v4
	v_fmac_f32_e32 v117, v244, v3
	v_mul_f32_e32 v116, v247, v6
	v_fmac_f32_e32 v116, v246, v5
	v_add_f32_e32 v116, v117, v116
	v_add_f32_e32 v83, v83, v116
	s_waitcnt lgkmcnt(4)
	v_mul_f32_e32 v116, v249, v16
	v_mul_f32_e32 v117, v251, v15
	v_fmac_f32_e32 v116, v248, v14
	v_fmac_f32_e32 v117, v250, v13
	v_add_f32_e32 v116, v116, v117
	v_add_f32_e32 v120, v83, v116
	v_mul_f32_e64 v83, |v120|, s64
	v_exp_f32_e32 v116, v83
	v_fmamk_f32 v81, v81, 0x3d800000, v80
	v_fmamk_f32 v82, v82, 0x3d800000, v81
	v_fmamk_f32 v83, v115, 0x3d800000, v82
	v_add_f32_e32 v116, 1.0, v116
	v_log_f32_e32 v121, v116
	ds_read_b128 v[236:239], v63 offset:3776
	v_min_f32_e32 v115, 0, v124
	v_min_f32_e32 v124, 0, v120
	v_fmac_f32_e32 v124, 0xbf317218, v121
	ds_read_b128 v[240:243], v63 offset:3792
	s_waitcnt lgkmcnt(5)
	v_mul_f32_e32 v117, v221, v2
	v_fmac_f32_e32 v117, v220, v17
	v_mul_f32_e32 v116, v223, v12
	v_fmac_f32_e32 v116, v222, v10
	v_add_f32_e32 v116, v117, v116
	s_waitcnt lgkmcnt(4)
	v_mul_f32_e32 v121, v225, v11
	v_fmac_f32_e32 v115, 0xbf317218, v125
	v_add_f32_e32 v125, v18, v116
	v_fmac_f32_e32 v121, v224, v8
	v_mul_f32_e32 v120, v227, v9
	ds_read_b128 v[244:247], v63 offset:3808
	v_fmac_f32_e32 v120, v226, v7
	v_add_f32_e32 v120, v121, v120
	v_add_f32_e32 v125, v125, v120
	ds_read_b128 v[248:251], v63 offset:3824
	s_waitcnt lgkmcnt(5)
	v_mul_f32_e32 v117, v229, v4
	v_fmac_f32_e32 v117, v228, v3
	v_mul_f32_e32 v116, v231, v6
	v_fmac_f32_e32 v116, v230, v5
	v_add_f32_e32 v116, v117, v116
	s_waitcnt lgkmcnt(4)
	v_mul_f32_e32 v117, v233, v16
	v_mul_f32_e32 v118, v235, v15
	v_fmac_f32_e32 v117, v232, v14
	v_fmac_f32_e32 v118, v234, v13
	v_add_f32_e32 v116, v125, v116
	v_add_f32_e32 v117, v117, v118
	v_add_f32_e32 v117, v116, v117
	v_mul_f32_e64 v116, |v117|, s64
	v_exp_f32_e32 v122, v116
	ds_read_b128 v[220:223], v63 offset:3840
	v_fmamk_f32 v115, v115, 0x3d800000, v83
	v_fmamk_f32 v116, v124, 0x3d800000, v115
	v_add_f32_e32 v122, 1.0, v122
	v_log_f32_e32 v126, v122
	ds_read_b128 v[224:227], v63 offset:3856
	s_waitcnt lgkmcnt(5)
	v_mul_f32_e32 v119, v237, v2
	v_fmac_f32_e32 v119, v236, v17
	v_mul_f32_e32 v118, v239, v12
	v_fmac_f32_e32 v118, v238, v10
	v_add_f32_e32 v118, v119, v118
	s_waitcnt lgkmcnt(4)
	v_mul_f32_e32 v123, v241, v11
	v_add_f32_e32 v127, v18, v118
	v_fmac_f32_e32 v123, v240, v8
	v_mul_f32_e32 v122, v243, v9
	ds_read_b128 v[228:231], v63 offset:3872
	v_fmac_f32_e32 v122, v242, v7
	v_add_f32_e32 v122, v123, v122
	v_add_f32_e32 v127, v127, v122
	ds_read_b128 v[232:235], v63 offset:3888
	s_waitcnt lgkmcnt(5)
	v_mul_f32_e32 v119, v245, v4
	v_fmac_f32_e32 v119, v244, v3
	v_mul_f32_e32 v118, v247, v6
	v_fmac_f32_e32 v118, v246, v5
	v_add_f32_e32 v118, v119, v118
	s_waitcnt lgkmcnt(4)
	v_mul_f32_e32 v119, v249, v16
	v_mul_f32_e32 v120, v251, v15
	v_fmac_f32_e32 v119, v248, v14
	v_fmac_f32_e32 v120, v250, v13
	v_add_f32_e32 v118, v127, v118
	v_add_f32_e32 v119, v119, v120
	v_add_f32_e32 v127, v118, v119
	v_mul_f32_e64 v118, |v127|, s64
	v_exp_f32_e32 v122, v118
	ds_read_b128 v[236:239], v63 offset:3904
	v_min_f32_e32 v117, 0, v117
	v_fmac_f32_e32 v117, 0xbf317218, v126
	v_add_f32_e32 v122, 1.0, v122
	v_log_f32_e32 v126, v122
	ds_read_b128 v[240:243], v63 offset:3920
	s_waitcnt lgkmcnt(5)
	v_mul_f32_e32 v119, v221, v2
	v_fmac_f32_e32 v119, v220, v17
	v_mul_f32_e32 v118, v223, v12
	v_fmac_f32_e32 v118, v222, v10
	v_add_f32_e32 v118, v119, v118
	s_waitcnt lgkmcnt(4)
	v_mul_f32_e32 v123, v225, v11
	v_add_f32_e32 v128, v18, v118
	v_fmac_f32_e32 v123, v224, v8
	v_mul_f32_e32 v122, v227, v9
	ds_read_b128 v[244:247], v63 offset:3936
	v_fmac_f32_e32 v122, v226, v7
	v_add_f32_e32 v122, v123, v122
	v_add_f32_e32 v128, v128, v122
	ds_read_b128 v[248:251], v63 offset:3952
	s_waitcnt lgkmcnt(5)
	v_mul_f32_e32 v119, v229, v4
	v_fmac_f32_e32 v119, v228, v3
	v_mul_f32_e32 v118, v231, v6
	v_fmac_f32_e32 v118, v230, v5
	v_add_f32_e32 v118, v119, v118
	s_waitcnt lgkmcnt(4)
	v_mul_f32_e32 v119, v233, v16
	v_mul_f32_e32 v120, v235, v15
	v_fmac_f32_e32 v119, v232, v14
	v_fmac_f32_e32 v120, v234, v13
	v_add_f32_e32 v118, v128, v118
	v_add_f32_e32 v119, v119, v120
	v_add_f32_e32 v128, v118, v119
	v_mul_f32_e64 v118, |v128|, s64
	v_exp_f32_e32 v122, v118
	ds_read_b128 v[220:223], v63 offset:3968
	v_min_f32_e32 v127, 0, v127
	v_fmac_f32_e32 v127, 0xbf317218, v126
	v_add_f32_e32 v122, 1.0, v122
	v_log_f32_e32 v126, v122
	ds_read_b128 v[224:227], v63 offset:3984
	s_waitcnt lgkmcnt(5)
	v_mul_f32_e32 v119, v237, v2
	v_fmac_f32_e32 v119, v236, v17
	v_mul_f32_e32 v118, v239, v12
	v_fmac_f32_e32 v118, v238, v10
	v_add_f32_e32 v118, v119, v118
	s_waitcnt lgkmcnt(4)
	v_mul_f32_e32 v123, v241, v11
	v_add_f32_e32 v129, v18, v118
	v_fmac_f32_e32 v123, v240, v8
	v_mul_f32_e32 v122, v243, v9
	ds_read_b128 v[228:231], v63 offset:4000
	v_fmac_f32_e32 v122, v242, v7
	v_add_f32_e32 v122, v123, v122
	v_add_f32_e32 v129, v129, v122
	ds_read_b128 v[232:235], v63 offset:4016
	s_waitcnt lgkmcnt(5)
	v_mul_f32_e32 v119, v245, v4
	v_fmac_f32_e32 v119, v244, v3
	v_mul_f32_e32 v118, v247, v6
	v_fmac_f32_e32 v118, v246, v5
	v_add_f32_e32 v118, v119, v118
	s_waitcnt lgkmcnt(4)
	v_mul_f32_e32 v119, v249, v16
	v_mul_f32_e32 v120, v251, v15
	v_fmac_f32_e32 v119, v248, v14
	v_fmac_f32_e32 v120, v250, v13
	v_add_f32_e32 v118, v129, v118
	v_add_f32_e32 v119, v119, v120
	v_add_f32_e32 v122, v118, v119
	v_mul_f32_e64 v118, |v122|, s64
	v_exp_f32_e32 v118, v118
	v_fmamk_f32 v117, v117, 0x3d800000, v116
	v_min_f32_e32 v119, 0, v128
	v_fmamk_f32 v127, v127, 0x3d800000, v117
	v_add_f32_e32 v118, 1.0, v118
	v_fmac_f32_e32 v119, 0xbf317218, v126
	v_log_f32_e32 v123, v118
	v_fmamk_f32 v126, v119, 0x3d800000, v127
	ds_read_b128 v[236:239], v63 offset:4032
	v_min_f32_e32 v122, 0, v122
	v_fmac_f32_e32 v122, 0xbf317218, v123
	v_fmamk_f32 v128, v122, 0x3d800000, v126
	ds_read_b128 v[240:243], v63 offset:4048
	s_waitcnt lgkmcnt(5)
	v_mul_f32_e32 v119, v221, v2
	v_fmac_f32_e32 v119, v220, v17
	v_mul_f32_e32 v118, v223, v12
	v_fmac_f32_e32 v118, v222, v10
	v_add_f32_e32 v118, v119, v118
	v_add_f32_e32 v129, v18, v118
	s_waitcnt lgkmcnt(4)
	v_mul_f32_e32 v123, v225, v11
	ds_read_b128 v[244:247], v63 offset:4064
	v_fmac_f32_e32 v123, v224, v8
	v_mul_f32_e32 v122, v227, v9
	v_fmac_f32_e32 v122, v226, v7
	v_add_f32_e32 v122, v123, v122
	v_add_f32_e32 v129, v129, v122
	ds_read_b128 v[248:251], v63 offset:4080
	s_waitcnt lgkmcnt(5)
	v_mul_f32_e32 v119, v229, v4
	v_fmac_f32_e32 v119, v228, v3
	v_mul_f32_e32 v118, v231, v6
	v_fmac_f32_e32 v118, v230, v5
	v_add_f32_e32 v118, v119, v118
	v_add_f32_e32 v129, v129, v118
	s_waitcnt lgkmcnt(4)
	v_mul_f32_e32 v118, v233, v16
	v_mul_f32_e32 v119, v235, v15
	v_fmac_f32_e32 v118, v232, v14
	v_fmac_f32_e32 v119, v234, v13
	v_add_f32_e32 v122, v118, v119
	v_add_f32_e32 v129, v129, v122
	v_mul_f32_e64 v122, |v129|, s64
	v_exp_f32_e32 v130, v122
	s_waitcnt lgkmcnt(3)
	v_mul_f32_e32 v2, v237, v2
	v_mul_f32_e32 v12, v239, v12
	v_fmac_f32_e32 v2, v236, v17
	v_fmac_f32_e32 v12, v238, v10
	v_add_f32_e32 v2, v2, v12
	s_waitcnt lgkmcnt(2)
	v_mul_f32_e32 v12, v241, v11
	v_fmac_f32_e32 v12, v240, v8
	v_mul_f32_e32 v17, v243, v9
	v_fmac_f32_e32 v17, v242, v7
	v_add_f32_e32 v2, v18, v2
	v_add_f32_e32 v7, v12, v17
	s_waitcnt lgkmcnt(1)
	v_mul_f32_e32 v4, v245, v4
	v_fmac_f32_e32 v4, v244, v3
	v_mul_f32_e32 v3, v247, v6
	v_fmac_f32_e32 v3, v246, v5
	v_add_f32_e32 v2, v2, v7
	v_add_f32_e32 v3, v4, v3
	v_add_f32_e32 v2, v2, v3
	s_waitcnt lgkmcnt(0)
	v_mul_f32_e32 v3, v249, v16
	v_mul_f32_e32 v4, v251, v15
	v_fmac_f32_e32 v3, v248, v14
	v_fmac_f32_e32 v4, v250, v13
	v_add_f32_e32 v3, v3, v4
	v_add_f32_e32 v2, v2, v3
	v_mul_f32_e64 v3, |v2|, s64
	v_exp_f32_e32 v3, v3
	v_add_f32_e32 v4, 1.0, v130
	v_log_f32_e32 v4, v4
	v_min_f32_e32 v5, 0, v129
	v_add_f32_e32 v3, 1.0, v3
	v_log_f32_e32 v3, v3
	v_fmac_f32_e32 v5, 0xbf317218, v4
	v_min_f32_e32 v2, 0, v2
	v_fmamk_f32 v118, v5, 0x3d800000, v128
	v_fmac_f32_e32 v2, 0xbf317218, v3
	v_fmamk_f32 v119, v2, 0x3d800000, v118
	ds_write_b32 v87, v119 offset:16384
	s_waitcnt lgkmcnt(0)
	s_barrier
	ds_read2st64_b32 v[2:3], v85 offset0:64 offset1:66
	ds_read2st64_b32 v[4:5], v85 offset0:68 offset1:70
	s_waitcnt lgkmcnt(1)
	v_add_f32_e32 v2, 0, v2
	v_cndmask_b32_e64 v6, v2, 0, s[24:25]
	v_add_f32_e32 v7, v6, v3
	v_cndmask_b32_e64 v6, v6, v7, s[4:5]
	s_waitcnt lgkmcnt(0)
	v_add_f32_e32 v7, v6, v4
	v_cndmask_b32_e64 v6, v6, v7, s[6:7]
	v_add_f32_e32 v7, v6, v5
	v_cndmask_b32_e64 v120, v6, v7, s[8:9]
	v_add_f32_e32 v82, v120, v82
	v_add_f32_e32 v167, v120, v64
	v_mul_f32_e32 v64, 0xbfb8aa3b, v82
	v_min_f32_e32 v64, 0x42e60000, v64
	v_add_f32_e32 v83, v120, v83
	v_add_f32_e32 v168, v120, v72
	v_exp_f32_e32 v72, v64
	v_mul_f32_e32 v64, 0xbfb8aa3b, v83
	v_min_f32_e32 v64, 0x42e60000, v64
	v_add_f32_e32 v178, v120, v115
	v_add_f32_e32 v169, v120, v73
	v_exp_f32_e32 v73, v64
	v_mul_f32_e32 v64, 0xbfb8aa3b, v178
	v_min_f32_e32 v64, 0x42e60000, v64
	v_add_f32_e32 v179, v120, v116
	v_add_f32_e32 v170, v120, v74
	v_exp_f32_e32 v74, v64
	v_mul_f32_e32 v64, 0xbfb8aa3b, v179
	v_min_f32_e32 v64, 0x42e60000, v64
	v_add_f32_e32 v180, v120, v117
	v_add_f32_e32 v171, v120, v75
	v_exp_f32_e32 v75, v64
	v_mul_f32_e32 v64, 0xbfb8aa3b, v180
	v_min_f32_e32 v64, 0x42e60000, v64
	v_add_f32_e32 v181, v120, v127
	v_add_f32_e32 v172, v120, v76
	v_exp_f32_e32 v76, v64
	v_mul_f32_e32 v64, 0xbfb8aa3b, v181
	v_mul_f32_e32 v82, 0x3fb8aa3b, v82
	v_mul_f32_e32 v83, 0x3fb8aa3b, v83
	v_min_f32_e32 v64, 0x42e60000, v64
	v_add_f32_e32 v182, v120, v126
	v_exp_f32_e32 v82, v82
	v_exp_f32_e32 v83, v83
	v_add_f32_e32 v173, v120, v77
	v_exp_f32_e32 v77, v64
	v_mul_f32_e32 v64, 0xbfb8aa3b, v182
	v_min_f32_e32 v64, 0x42e60000, v64
	v_add_f32_e32 v183, v120, v128
	v_add_f32_e32 v129, v120, v24
	v_add_f32_e32 v138, v120, v33
	v_add_f32_e32 v139, v120, v34
	v_add_f32_e32 v148, v120, v43
	v_add_f32_e32 v149, v120, v44
	v_add_f32_e32 v158, v120, v53
	v_add_f32_e32 v159, v120, v54
	v_add_f32_e32 v174, v120, v78
	v_exp_f32_e32 v78, v64
	v_mul_f32_e32 v64, 0xbfb8aa3b, v183
	v_add_f32_e32 v124, v120, v22
	v_add_f32_e32 v125, v120, v23
	v_mul_f32_e32 v13, 0xbfb8aa3b, v129
	v_add_f32_e32 v137, v120, v32
	v_mul_f32_e32 v22, 0xbfb8aa3b, v138
	v_mul_f32_e32 v23, 0xbfb8aa3b, v139
	v_add_f32_e32 v147, v120, v42
	v_mul_f32_e32 v32, 0xbfb8aa3b, v148
	v_mul_f32_e32 v33, 0xbfb8aa3b, v149
	v_add_f32_e32 v157, v120, v52
	v_mul_f32_e32 v42, 0xbfb8aa3b, v158
	v_mul_f32_e32 v43, 0xbfb8aa3b, v159
	v_mul_f32_e32 v52, 0xbfb8aa3b, v168
	v_mul_f32_e32 v53, 0xbfb8aa3b, v169
	v_min_f32_e32 v64, 0x42e60000, v64
	v_add_f32_e32 v184, v120, v118
	v_add_f32_e32 v185, v120, v119
	v_mul_f32_e32 v119, 0x3fb8aa3b, v129
	v_mul_f32_e32 v128, 0x3fb8aa3b, v138
	v_mul_f32_e32 v129, 0x3fb8aa3b, v139
	v_mul_f32_e32 v138, 0x3fb8aa3b, v148
	v_mul_f32_e32 v139, 0x3fb8aa3b, v149
	v_mul_f32_e32 v148, 0x3fb8aa3b, v158
	v_mul_f32_e32 v149, 0x3fb8aa3b, v159
	v_mul_f32_e32 v158, 0x3fb8aa3b, v168
	v_mul_f32_e32 v159, 0x3fb8aa3b, v169
	v_mul_f32_e32 v168, 0x3db504f3, v82
	v_mul_f32_e32 v169, 0x3db504f3, v83
	v_mul_f32_e32 v82, 0x3fb8aa3b, v178
	v_mul_f32_e32 v83, 0x3fb8aa3b, v179
	v_add_f32_e32 v175, v120, v79
	v_exp_f32_e32 v79, v64
	v_mul_f32_e32 v64, 0xbfb8aa3b, v184
	v_exp_f32_e32 v82, v82
	v_exp_f32_e32 v83, v83
	v_add_f32_e32 v130, v120, v25
	v_add_f32_e32 v140, v120, v35
	v_add_f32_e32 v150, v120, v45
	v_add_f32_e32 v160, v120, v55
	v_min_f32_e32 v64, 0x42e60000, v64
	v_add_f32_e32 v121, v120, v19
	v_add_f32_e32 v122, v120, v20
	v_add_f32_e32 v123, v120, v21
	v_mul_f32_e32 v14, 0xbfb8aa3b, v130
	v_add_f32_e32 v131, v120, v26
	v_add_f32_e32 v132, v120, v27
	v_add_f32_e32 v133, v120, v28
	v_add_f32_e32 v134, v120, v29
	v_add_f32_e32 v135, v120, v30
	v_add_f32_e32 v136, v120, v31
	v_mul_f32_e32 v24, 0xbfb8aa3b, v140
	v_add_f32_e32 v141, v120, v36
	v_add_f32_e32 v142, v120, v37
	v_add_f32_e32 v143, v120, v38
	v_add_f32_e32 v144, v120, v39
	v_add_f32_e32 v145, v120, v40
	v_add_f32_e32 v146, v120, v41
	v_mul_f32_e32 v34, 0xbfb8aa3b, v150
	v_add_f32_e32 v151, v120, v46
	v_add_f32_e32 v152, v120, v47
	v_add_f32_e32 v153, v120, v48
	v_add_f32_e32 v154, v120, v49
	v_add_f32_e32 v155, v120, v50
	v_add_f32_e32 v156, v120, v51
	v_mul_f32_e32 v44, 0xbfb8aa3b, v160
	v_add_f32_e32 v161, v120, v56
	v_add_f32_e32 v162, v120, v57
	v_add_f32_e32 v163, v120, v58
	v_add_f32_e32 v164, v120, v59
	v_add_f32_e32 v165, v120, v60
	v_add_f32_e32 v166, v120, v61
	v_mul_f32_e32 v54, 0xbfb8aa3b, v170
	v_add_f32_e32 v176, v120, v80
	v_add_f32_e32 v177, v120, v81
	v_exp_f32_e32 v80, v64
	v_mul_f32_e32 v64, 0xbfb8aa3b, v185
	v_mul_f32_e32 v120, 0x3fb8aa3b, v130
	v_mul_f32_e32 v130, 0x3fb8aa3b, v140
	v_mul_f32_e32 v140, 0x3fb8aa3b, v150
	v_mul_f32_e32 v150, 0x3fb8aa3b, v160
	v_mul_f32_e32 v160, 0x3fb8aa3b, v170
	v_mul_f32_e32 v170, 0x3fb8aa3b, v180
	v_mul_f32_e32 v9, 0xbfb8aa3b, v122
	v_mul_f32_e32 v11, 0xbfb8aa3b, v124
	v_mul_f32_e32 v16, 0xbfb8aa3b, v132
	v_mul_f32_e32 v18, 0xbfb8aa3b, v134
	v_mul_f32_e32 v26, 0xbfb8aa3b, v142
	v_mul_f32_e32 v28, 0xbfb8aa3b, v144
	v_mul_f32_e32 v36, 0xbfb8aa3b, v152
	v_mul_f32_e32 v38, 0xbfb8aa3b, v154
	v_mul_f32_e32 v46, 0xbfb8aa3b, v162
	v_mul_f32_e32 v48, 0xbfb8aa3b, v164
	v_mul_f32_e32 v56, 0xbfb8aa3b, v172
	v_mul_f32_e32 v58, 0xbfb8aa3b, v174
	v_min_f32_e32 v64, 0x42e60000, v64
	v_mul_f32_e32 v115, 0x3fb8aa3b, v122
	v_mul_f32_e32 v117, 0x3fb8aa3b, v124
	v_mul_f32_e32 v122, 0x3fb8aa3b, v132
	v_mul_f32_e32 v124, 0x3fb8aa3b, v134
	v_mul_f32_e32 v132, 0x3fb8aa3b, v142
	v_mul_f32_e32 v134, 0x3fb8aa3b, v144
	v_mul_f32_e32 v142, 0x3fb8aa3b, v152
	v_mul_f32_e32 v144, 0x3fb8aa3b, v154
	v_mul_f32_e32 v152, 0x3fb8aa3b, v162
	v_mul_f32_e32 v154, 0x3fb8aa3b, v164
	v_mul_f32_e32 v162, 0x3fb8aa3b, v172
	v_mul_f32_e32 v164, 0x3fb8aa3b, v174
	v_exp_f32_e32 v172, v170
	v_mul_f32_e32 v170, 0x3fb8aa3b, v181
	v_mul_f32_e32 v174, 0x3fb8aa3b, v184
	v_mul_f32_e32 v8, 0xbfb8aa3b, v121
	v_mul_f32_e32 v10, 0xbfb8aa3b, v123
	v_mul_f32_e32 v12, 0xbfb8aa3b, v125
	v_mul_f32_e32 v15, 0xbfb8aa3b, v131
	v_mul_f32_e32 v17, 0xbfb8aa3b, v133
	v_mul_f32_e32 v19, 0xbfb8aa3b, v135
	v_mul_f32_e32 v20, 0xbfb8aa3b, v136
	v_mul_f32_e32 v21, 0xbfb8aa3b, v137
	v_mul_f32_e32 v25, 0xbfb8aa3b, v141
	v_mul_f32_e32 v27, 0xbfb8aa3b, v143
	v_mul_f32_e32 v29, 0xbfb8aa3b, v145
	v_mul_f32_e32 v30, 0xbfb8aa3b, v146
	v_mul_f32_e32 v31, 0xbfb8aa3b, v147
	v_mul_f32_e32 v35, 0xbfb8aa3b, v151
	v_mul_f32_e32 v37, 0xbfb8aa3b, v153
	v_mul_f32_e32 v39, 0xbfb8aa3b, v155
	v_mul_f32_e32 v40, 0xbfb8aa3b, v156
	v_mul_f32_e32 v41, 0xbfb8aa3b, v157
	v_mul_f32_e32 v45, 0xbfb8aa3b, v161
	v_mul_f32_e32 v47, 0xbfb8aa3b, v163
	v_mul_f32_e32 v49, 0xbfb8aa3b, v165
	v_mul_f32_e32 v50, 0xbfb8aa3b, v166
	v_mul_f32_e32 v51, 0xbfb8aa3b, v167
	v_mul_f32_e32 v55, 0xbfb8aa3b, v171
	v_mul_f32_e32 v57, 0xbfb8aa3b, v173
	v_mul_f32_e32 v59, 0xbfb8aa3b, v175
	v_mul_f32_e32 v60, 0xbfb8aa3b, v176
	v_mul_f32_e32 v61, 0xbfb8aa3b, v177
	v_exp_f32_e32 v81, v64
	v_mul_f32_e32 v64, 0x3fb8aa3b, v121
	v_mul_f32_e32 v116, 0x3fb8aa3b, v123
	v_mul_f32_e32 v118, 0x3fb8aa3b, v125
	v_mul_f32_e32 v121, 0x3fb8aa3b, v131
	v_mul_f32_e32 v123, 0x3fb8aa3b, v133
	v_mul_f32_e32 v125, 0x3fb8aa3b, v135
	v_mul_f32_e32 v126, 0x3fb8aa3b, v136
	v_mul_f32_e32 v127, 0x3fb8aa3b, v137
	v_mul_f32_e32 v131, 0x3fb8aa3b, v141
	v_mul_f32_e32 v133, 0x3fb8aa3b, v143
	v_mul_f32_e32 v135, 0x3fb8aa3b, v145
	v_mul_f32_e32 v136, 0x3fb8aa3b, v146
	v_mul_f32_e32 v137, 0x3fb8aa3b, v147
	v_mul_f32_e32 v141, 0x3fb8aa3b, v151
	v_mul_f32_e32 v143, 0x3fb8aa3b, v153
	v_mul_f32_e32 v145, 0x3fb8aa3b, v155
	v_mul_f32_e32 v146, 0x3fb8aa3b, v156
	v_mul_f32_e32 v147, 0x3fb8aa3b, v157
	v_mul_f32_e32 v151, 0x3fb8aa3b, v161
	v_mul_f32_e32 v153, 0x3fb8aa3b, v163
	v_mul_f32_e32 v155, 0x3fb8aa3b, v165
	v_mul_f32_e32 v156, 0x3fb8aa3b, v166
	v_mul_f32_e32 v157, 0x3fb8aa3b, v167
	v_mul_f32_e32 v161, 0x3fb8aa3b, v171
	v_mul_f32_e32 v163, 0x3fb8aa3b, v173
	v_mul_f32_e32 v165, 0x3fb8aa3b, v175
	v_mul_f32_e32 v166, 0x3fb8aa3b, v176
	v_mul_f32_e32 v167, 0x3fb8aa3b, v177
	v_exp_f32_e32 v173, v170
	v_mul_f32_e32 v170, 0x3db504f3, v82
	v_mul_f32_e32 v171, 0x3db504f3, v83
	v_mul_f32_e32 v82, 0x3fb8aa3b, v182
	v_mul_f32_e32 v83, 0x3fb8aa3b, v183
	v_exp_f32_e32 v176, v174
	v_mul_f32_e32 v174, 0x3fb8aa3b, v185
	v_min_f32_e32 v8, 0x42e60000, v8
	v_min_f32_e32 v9, 0x42e60000, v9
	v_min_f32_e32 v10, 0x42e60000, v10
	v_min_f32_e32 v11, 0x42e60000, v11
	v_min_f32_e32 v12, 0x42e60000, v12
	v_min_f32_e32 v13, 0x42e60000, v13
	v_min_f32_e32 v14, 0x42e60000, v14
	v_min_f32_e32 v15, 0x42e60000, v15
	v_min_f32_e32 v16, 0x42e60000, v16
	v_min_f32_e32 v17, 0x42e60000, v17
	v_min_f32_e32 v18, 0x42e60000, v18
	v_min_f32_e32 v19, 0x42e60000, v19
	v_min_f32_e32 v20, 0x42e60000, v20
	v_min_f32_e32 v21, 0x42e60000, v21
	v_min_f32_e32 v22, 0x42e60000, v22
	v_min_f32_e32 v23, 0x42e60000, v23
	v_min_f32_e32 v24, 0x42e60000, v24
	v_min_f32_e32 v25, 0x42e60000, v25
	v_min_f32_e32 v26, 0x42e60000, v26
	v_min_f32_e32 v27, 0x42e60000, v27
	v_min_f32_e32 v28, 0x42e60000, v28
	v_min_f32_e32 v29, 0x42e60000, v29
	v_min_f32_e32 v30, 0x42e60000, v30
	v_min_f32_e32 v31, 0x42e60000, v31
	v_min_f32_e32 v32, 0x42e60000, v32
	v_min_f32_e32 v33, 0x42e60000, v33
	v_min_f32_e32 v34, 0x42e60000, v34
	v_min_f32_e32 v35, 0x42e60000, v35
	v_min_f32_e32 v36, 0x42e60000, v36
	v_min_f32_e32 v37, 0x42e60000, v37
	v_min_f32_e32 v38, 0x42e60000, v38
	v_min_f32_e32 v39, 0x42e60000, v39
	v_min_f32_e32 v40, 0x42e60000, v40
	v_min_f32_e32 v41, 0x42e60000, v41
	v_min_f32_e32 v42, 0x42e60000, v42
	v_min_f32_e32 v43, 0x42e60000, v43
	v_min_f32_e32 v44, 0x42e60000, v44
	v_min_f32_e32 v45, 0x42e60000, v45
	v_min_f32_e32 v46, 0x42e60000, v46
	v_min_f32_e32 v47, 0x42e60000, v47
	v_min_f32_e32 v48, 0x42e60000, v48
	v_min_f32_e32 v49, 0x42e60000, v49
	v_min_f32_e32 v50, 0x42e60000, v50
	v_min_f32_e32 v51, 0x42e60000, v51
	v_min_f32_e32 v52, 0x42e60000, v52
	v_min_f32_e32 v53, 0x42e60000, v53
	v_min_f32_e32 v54, 0x42e60000, v54
	v_min_f32_e32 v55, 0x42e60000, v55
	v_min_f32_e32 v56, 0x42e60000, v56
	v_min_f32_e32 v57, 0x42e60000, v57
	v_min_f32_e32 v58, 0x42e60000, v58
	v_min_f32_e32 v59, 0x42e60000, v59
	v_min_f32_e32 v60, 0x42e60000, v60
	v_min_f32_e32 v61, 0x42e60000, v61
	v_exp_f32_e32 v64, v64
	v_exp_f32_e32 v115, v115
	v_exp_f32_e32 v116, v116
	v_exp_f32_e32 v117, v117
	v_exp_f32_e32 v118, v118
	v_exp_f32_e32 v119, v119
	v_exp_f32_e32 v120, v120
	v_exp_f32_e32 v121, v121
	v_exp_f32_e32 v122, v122
	v_exp_f32_e32 v123, v123
	v_exp_f32_e32 v124, v124
	v_exp_f32_e32 v125, v125
	v_exp_f32_e32 v126, v126
	v_exp_f32_e32 v127, v127
	v_exp_f32_e32 v128, v128
	v_exp_f32_e32 v129, v129
	v_exp_f32_e32 v130, v130
	v_exp_f32_e32 v131, v131
	v_exp_f32_e32 v132, v132
	v_exp_f32_e32 v133, v133
	v_exp_f32_e32 v134, v134
	v_exp_f32_e32 v135, v135
	v_exp_f32_e32 v136, v136
	v_exp_f32_e32 v137, v137
	v_exp_f32_e32 v138, v138
	v_exp_f32_e32 v139, v139
	v_exp_f32_e32 v140, v140
	v_exp_f32_e32 v141, v141
	v_exp_f32_e32 v142, v142
	v_exp_f32_e32 v143, v143
	v_exp_f32_e32 v144, v144
	v_exp_f32_e32 v145, v145
	v_exp_f32_e32 v146, v146
	v_exp_f32_e32 v147, v147
	v_exp_f32_e32 v148, v148
	v_exp_f32_e32 v149, v149
	v_exp_f32_e32 v150, v150
	v_exp_f32_e32 v151, v151
	v_exp_f32_e32 v152, v152
	v_exp_f32_e32 v153, v153
	v_exp_f32_e32 v154, v154
	v_exp_f32_e32 v155, v155
	v_exp_f32_e32 v156, v156
	v_exp_f32_e32 v157, v157
	v_exp_f32_e32 v158, v158
	v_exp_f32_e32 v159, v159
	v_exp_f32_e32 v160, v160
	v_exp_f32_e32 v161, v161
	v_exp_f32_e32 v162, v162
	v_exp_f32_e32 v163, v163
	v_exp_f32_e32 v164, v164
	v_exp_f32_e32 v165, v165
	v_exp_f32_e32 v166, v166
	v_exp_f32_e32 v167, v167
	v_exp_f32_e32 v82, v82
	v_exp_f32_e32 v83, v83
	v_exp_f32_e32 v177, v174
	v_lshl_add_u32 v6, s46, 8, v88
	v_exp_f32_e32 v8, v8
	v_exp_f32_e32 v9, v9
	v_exp_f32_e32 v10, v10
	v_exp_f32_e32 v11, v11
	v_exp_f32_e32 v12, v12
	v_exp_f32_e32 v13, v13
	v_exp_f32_e32 v14, v14
	v_exp_f32_e32 v15, v15
	v_exp_f32_e32 v16, v16
	v_exp_f32_e32 v17, v17
	v_exp_f32_e32 v18, v18
	v_exp_f32_e32 v19, v19
	v_exp_f32_e32 v20, v20
	v_exp_f32_e32 v21, v21
	v_exp_f32_e32 v22, v22
	v_exp_f32_e32 v23, v23
	v_exp_f32_e32 v24, v24
	v_exp_f32_e32 v25, v25
	v_exp_f32_e32 v26, v26
	v_exp_f32_e32 v27, v27
	v_exp_f32_e32 v28, v28
	v_exp_f32_e32 v29, v29
	v_exp_f32_e32 v30, v30
	v_exp_f32_e32 v31, v31
	v_exp_f32_e32 v32, v32
	v_exp_f32_e32 v33, v33
	v_exp_f32_e32 v34, v34
	v_exp_f32_e32 v35, v35
	v_exp_f32_e32 v36, v36
	v_exp_f32_e32 v37, v37
	v_exp_f32_e32 v38, v38
	v_exp_f32_e32 v39, v39
	v_exp_f32_e32 v40, v40
	v_exp_f32_e32 v41, v41
	v_exp_f32_e32 v42, v42
	v_exp_f32_e32 v43, v43
	v_exp_f32_e32 v44, v44
	v_exp_f32_e32 v45, v45
	v_exp_f32_e32 v46, v46
	v_exp_f32_e32 v47, v47
	v_exp_f32_e32 v48, v48
	v_exp_f32_e32 v49, v49
	v_exp_f32_e32 v50, v50
	v_exp_f32_e32 v51, v51
	v_exp_f32_e32 v52, v52
	v_exp_f32_e32 v53, v53
	v_exp_f32_e32 v54, v54
	v_exp_f32_e32 v55, v55
	v_exp_f32_e32 v56, v56
	v_exp_f32_e32 v57, v57
	v_exp_f32_e32 v58, v58
	v_exp_f32_e32 v59, v59
	v_exp_f32_e32 v60, v60
	v_exp_f32_e32 v61, v61
	v_mad_i64_i32 v[6:7], s[48:49], v6, s66, v[68:69]
	v_lshl_add_u64 v[6:7], v[6:7], 0, s[0:1]
	v_lshl_add_u64 v[6:7], v[6:7], 0, v[70:71]
	v_mul_f32_e32 v64, 0x3db504f3, v64
	v_mul_f32_e32 v115, 0x3db504f3, v115
	v_mul_f32_e32 v116, 0x3db504f3, v116
	v_mul_f32_e32 v117, 0x3db504f3, v117
	v_mul_f32_e32 v118, 0x3db504f3, v118
	v_mul_f32_e32 v119, 0x3db504f3, v119
	v_mul_f32_e32 v120, 0x3db504f3, v120
	v_mul_f32_e32 v121, 0x3db504f3, v121
	v_mul_f32_e32 v122, 0x3db504f3, v122
	v_mul_f32_e32 v123, 0x3db504f3, v123
	v_mul_f32_e32 v124, 0x3db504f3, v124
	v_mul_f32_e32 v125, 0x3db504f3, v125
	v_mul_f32_e32 v126, 0x3db504f3, v126
	v_mul_f32_e32 v127, 0x3db504f3, v127
	v_mul_f32_e32 v128, 0x3db504f3, v128
	v_mul_f32_e32 v129, 0x3db504f3, v129
	v_mul_f32_e32 v130, 0x3db504f3, v130
	v_mul_f32_e32 v131, 0x3db504f3, v131
	v_mul_f32_e32 v132, 0x3db504f3, v132
	v_mul_f32_e32 v133, 0x3db504f3, v133
	v_mul_f32_e32 v134, 0x3db504f3, v134
	v_mul_f32_e32 v135, 0x3db504f3, v135
	v_mul_f32_e32 v136, 0x3db504f3, v136
	v_mul_f32_e32 v137, 0x3db504f3, v137
	v_mul_f32_e32 v138, 0x3db504f3, v138
	v_mul_f32_e32 v139, 0x3db504f3, v139
	v_mul_f32_e32 v140, 0x3db504f3, v140
	v_mul_f32_e32 v141, 0x3db504f3, v141
	v_mul_f32_e32 v142, 0x3db504f3, v142
	v_mul_f32_e32 v143, 0x3db504f3, v143
	v_mul_f32_e32 v144, 0x3db504f3, v144
	v_mul_f32_e32 v145, 0x3db504f3, v145
	v_mul_f32_e32 v146, 0x3db504f3, v146
	v_mul_f32_e32 v147, 0x3db504f3, v147
	v_mul_f32_e32 v148, 0x3db504f3, v148
	v_mul_f32_e32 v149, 0x3db504f3, v149
	v_mul_f32_e32 v150, 0x3db504f3, v150
	v_mul_f32_e32 v151, 0x3db504f3, v151
	v_mul_f32_e32 v152, 0x3db504f3, v152
	v_mul_f32_e32 v153, 0x3db504f3, v153
	v_mul_f32_e32 v154, 0x3db504f3, v154
	v_mul_f32_e32 v155, 0x3db504f3, v155
	v_mul_f32_e32 v156, 0x3db504f3, v156
	v_mul_f32_e32 v157, 0x3db504f3, v157
	v_mul_f32_e32 v158, 0x3db504f3, v158
	v_mul_f32_e32 v159, 0x3db504f3, v159
	v_mul_f32_e32 v160, 0x3db504f3, v160
	v_mul_f32_e32 v161, 0x3db504f3, v161
	v_mul_f32_e32 v162, 0x3db504f3, v162
	v_mul_f32_e32 v163, 0x3db504f3, v163
	v_mul_f32_e32 v164, 0x3db504f3, v164
	v_mul_f32_e32 v165, 0x3db504f3, v165
	v_mul_f32_e32 v166, 0x3db504f3, v166
	v_mul_f32_e32 v167, 0x3db504f3, v167
	v_mul_f32_e32 v172, 0x3db504f3, v172
	v_mul_f32_e32 v173, 0x3db504f3, v173
	v_mul_f32_e32 v174, 0x3db504f3, v82
	v_mul_f32_e32 v175, 0x3db504f3, v83
	v_mul_f32_e32 v176, 0x3db504f3, v176
	v_mul_f32_e32 v177, 0x3db504f3, v177
	s_mov_b64 s[48:49], -1
	s_branch .Lp2q_first
